# E33: K-loop load segments start with the ds_read fragment reads (B read addresses hoisted to loop-invariant v246..v249 in the preheader), SALU bookkeeping and LDS-DMA loads follow; applied to six of s
# speedup vs baseline: 1.0044x; 1.0009x over previous
.LBB0_188:
	s_ashr_i32 s21, s20, 31
	s_lshl_b64 s[22:23], s[20:21], 20
	s_add_u32 s22, s37, s22
	s_addc_u32 s23, s38, s23
	s_and_b64 s[24:25], s[4:5], exec
	s_cselect_b32 s21, s23, s29
	s_cselect_b32 s42, s22, s28
	s_ashr_i32 s19, s18, 31
	s_lshl_b64 s[24:25], s[18:19], 20
	s_add_u32 s24, s39, s24
	s_addc_u32 s25, s40, s25
	s_and_b64 s[34:35], s[4:5], exec
	s_cselect_b32 s19, s25, s31
	s_cselect_b32 s43, s24, s30
	s_add_u32 s28, s28, 0x80080
	s_addc_u32 s29, s29, 0
	s_add_u32 s62, s30, 0x100
	s_addc_u32 s63, s31, 0
	s_mov_b32 s66, -2
	v_mov_b32_e32 v0, v180
	v_mov_b32_e32 v1, v180
	v_mov_b32_e32 v2, v180
	v_mov_b32_e32 v3, v180
	v_mov_b32_e32 v4, v180
	v_mov_b32_e32 v5, v180
	v_mov_b32_e32 v6, v180
	v_mov_b32_e32 v7, v180
	v_mov_b32_e32 v16, v180
	v_mov_b32_e32 v17, v180
	v_mov_b32_e32 v18, v180
	v_mov_b32_e32 v19, v180
	v_mov_b32_e32 v20, v180
	v_mov_b32_e32 v21, v180
	v_mov_b32_e32 v22, v180
	v_mov_b32_e32 v23, v180
	v_mov_b32_e32 v32, v180
	v_mov_b32_e32 v33, v180
	v_mov_b32_e32 v34, v180
	v_mov_b32_e32 v35, v180
	v_mov_b32_e32 v36, v180
	v_mov_b32_e32 v37, v180
	v_mov_b32_e32 v38, v180
	v_mov_b32_e32 v39, v180
	v_mov_b32_e32 v48, v180
	v_mov_b32_e32 v49, v180
	v_mov_b32_e32 v50, v180
	v_mov_b32_e32 v51, v180
	v_mov_b32_e32 v52, v180
	v_mov_b32_e32 v53, v180
	v_mov_b32_e32 v54, v180
	v_mov_b32_e32 v55, v180
	v_mov_b32_e32 v8, v180
	v_mov_b32_e32 v9, v180
	v_mov_b32_e32 v10, v180
	v_mov_b32_e32 v11, v180
	v_mov_b32_e32 v12, v180
	v_mov_b32_e32 v13, v180
	v_mov_b32_e32 v14, v180
	v_mov_b32_e32 v15, v180
	v_mov_b32_e32 v24, v180
	v_mov_b32_e32 v25, v180
	v_mov_b32_e32 v26, v180
	v_mov_b32_e32 v27, v180
	v_mov_b32_e32 v28, v180
	v_mov_b32_e32 v29, v180
	v_mov_b32_e32 v30, v180
	v_mov_b32_e32 v31, v180
	v_mov_b32_e32 v40, v180
	v_mov_b32_e32 v41, v180
	v_mov_b32_e32 v42, v180
	v_mov_b32_e32 v43, v180
	v_mov_b32_e32 v44, v180
	v_mov_b32_e32 v45, v180
	v_mov_b32_e32 v46, v180
	v_mov_b32_e32 v47, v180
	v_mov_b32_e32 v56, v180
	v_mov_b32_e32 v57, v180
	v_mov_b32_e32 v58, v180
	v_mov_b32_e32 v59, v180
	v_mov_b32_e32 v60, v180
	v_mov_b32_e32 v61, v180
	v_mov_b32_e32 v62, v180
	v_mov_b32_e32 v63, v180
	v_mov_b32_e32 v68, v180
	v_mov_b32_e32 v69, v180
	v_mov_b32_e32 v70, v180
	v_mov_b32_e32 v71, v180
	v_mov_b32_e32 v76, v180
	v_mov_b32_e32 v77, v180
	v_mov_b32_e32 v78, v180
	v_mov_b32_e32 v79, v180
	v_mov_b32_e32 v96, v180
	v_mov_b32_e32 v97, v180
	v_mov_b32_e32 v98, v180
	v_mov_b32_e32 v99, v180
	v_mov_b32_e32 v100, v180
	v_mov_b32_e32 v101, v180
	v_mov_b32_e32 v102, v180
	v_mov_b32_e32 v103, v180
	v_mov_b32_e32 v112, v180
	v_mov_b32_e32 v113, v180
	v_mov_b32_e32 v114, v180
	v_mov_b32_e32 v115, v180
	v_mov_b32_e32 v116, v180
	v_mov_b32_e32 v117, v180
	v_mov_b32_e32 v118, v180
	v_mov_b32_e32 v119, v180
	v_mov_b32_e32 v128, v180
	v_mov_b32_e32 v129, v180
	v_mov_b32_e32 v130, v180
	v_mov_b32_e32 v131, v180
	v_mov_b32_e32 v132, v180
	v_mov_b32_e32 v133, v180
	v_mov_b32_e32 v134, v180
	v_mov_b32_e32 v135, v180
	v_mov_b32_e32 v88, v180
	v_mov_b32_e32 v89, v180
	v_mov_b32_e32 v90, v180
	v_mov_b32_e32 v91, v180
	v_mov_b32_e32 v92, v180
	v_mov_b32_e32 v93, v180
	v_mov_b32_e32 v94, v180
	v_mov_b32_e32 v95, v180
	v_mov_b32_e32 v104, v180
	v_mov_b32_e32 v105, v180
	v_mov_b32_e32 v106, v180
	v_mov_b32_e32 v107, v180
	v_mov_b32_e32 v108, v180
	v_mov_b32_e32 v109, v180
	v_mov_b32_e32 v110, v180
	v_mov_b32_e32 v111, v180
	v_mov_b32_e32 v120, v180
	v_mov_b32_e32 v121, v180
	v_mov_b32_e32 v122, v180
	v_mov_b32_e32 v123, v180
	v_mov_b32_e32 v124, v180
	v_mov_b32_e32 v125, v180
	v_mov_b32_e32 v126, v180
	v_mov_b32_e32 v127, v180
	v_mov_b32_e32 v136, v180
	v_mov_b32_e32 v137, v180
	v_mov_b32_e32 v138, v180
	v_mov_b32_e32 v139, v180
	v_mov_b32_e32 v140, v180
	v_mov_b32_e32 v141, v180
	v_mov_b32_e32 v142, v180
	v_mov_b32_e32 v143, v180
	s_waitcnt vmcnt(0)
	v_add_u32_e32 v246, 0x10000, v181
	v_add_u32_e32 v247, 0x14000, v181
	v_add_u32_e32 v248, 0x18000, v181
	v_add_u32_e32 v249, 0x1c000, v181
.LBB0_189:
	ds_read_b128 v[64:67], v246
	ds_read_b128 v[72:75], v246 offset:1024
	ds_read_b128 v[80:83], v246 offset:2048
	ds_read_b128 v[84:87], v246 offset:3072
	ds_read_b128 v[144:147], v247
	ds_read_b128 v[148:151], v247 offset:1024
	ds_read_b128 v[152:155], v247 offset:2048
	ds_read_b128 v[156:159], v247 offset:3072
	ds_read_b128 v[172:175], v182
	ds_read_b128 v[176:179], v182 offset:1024
	ds_read_b128 v[184:187], v182 offset:2048
	ds_read_b128 v[188:191], v182 offset:3072
	ds_read_b128 v[192:195], v182 offset:4096
	ds_read_b128 v[196:199], v182 offset:5120
	ds_read_b128 v[202:205], v182 offset:6144
	ds_read_b128 v[206:209], v182 offset:7168
	s_add_u32 s30, s28, 0xfff80080
	s_addc_u32 s31, s29, -1
	s_add_i32 s67, 0, 0x10000
	s_cmp_eq_u32 s66, 28
	s_cselect_b32 s35, s21, s31
	s_cselect_b32 s34, s42, s30
	s_cselect_b32 s31, s19, s63
	s_cselect_b32 s30, s43, s62
	s_add_i32 s70, 0, 0x14000
	v_lshl_add_u64 v[212:213], s[28:29], 0, v[168:169]
	s_add_i32 m0, s27, 0xc000
	s_nop 0
	global_load_lds_dwordx4 v[212:213], off
	v_lshl_add_u64 v[212:213], s[28:29], 0, v[170:171]
	s_add_i32 m0, s27, 0xe000
	s_nop 0
	global_load_lds_dwordx4 v[212:213], off
	s_waitcnt vmcnt(8)
	s_waitcnt lgkmcnt(0)
	s_setprio 1
	s_barrier
	v_mfma_f32_16x16x32_bf16 v[140:143], v[64:67], v[172:175], v[140:143]
	v_mfma_f32_16x16x32_bf16 v[136:139], v[80:83], v[172:175], v[136:139]
	v_mfma_f32_16x16x32_bf16 v[124:127], v[64:67], v[184:187], v[124:127]
	v_mfma_f32_16x16x32_bf16 v[120:123], v[80:83], v[184:187], v[120:123]
	v_mfma_f32_16x16x32_bf16 v[108:111], v[64:67], v[192:195], v[108:111]
	v_mfma_f32_16x16x32_bf16 v[104:107], v[80:83], v[192:195], v[104:107]
	v_mfma_f32_16x16x32_bf16 v[92:95], v[64:67], v[202:205], v[92:95]
	v_mfma_f32_16x16x32_bf16 v[88:91], v[80:83], v[202:205], v[88:91]
	v_mfma_f32_16x16x32_bf16 v[140:143], v[72:75], v[176:179], v[140:143]
	v_mfma_f32_16x16x32_bf16 v[136:139], v[84:87], v[176:179], v[136:139]
	v_mfma_f32_16x16x32_bf16 v[124:127], v[72:75], v[188:191], v[124:127]
	v_mfma_f32_16x16x32_bf16 v[120:123], v[84:87], v[188:191], v[120:123]
	v_mfma_f32_16x16x32_bf16 v[108:111], v[72:75], v[196:199], v[108:111]
	v_mfma_f32_16x16x32_bf16 v[104:107], v[84:87], v[196:199], v[104:107]
	v_mfma_f32_16x16x32_bf16 v[92:95], v[72:75], v[206:209], v[92:95]
	v_mfma_f32_16x16x32_bf16 v[88:91], v[84:87], v[206:209], v[88:91]
	s_setprio 0
	s_setprio 1
	v_mfma_f32_16x16x32_bf16 v[132:135], v[144:147], v[172:175], v[132:135]
	v_mfma_f32_16x16x32_bf16 v[128:131], v[152:155], v[172:175], v[128:131]
	v_mfma_f32_16x16x32_bf16 v[116:119], v[144:147], v[184:187], v[116:119]
	v_mfma_f32_16x16x32_bf16 v[112:115], v[152:155], v[184:187], v[112:115]
	v_mfma_f32_16x16x32_bf16 v[100:103], v[144:147], v[192:195], v[100:103]
	v_mfma_f32_16x16x32_bf16 v[96:99], v[152:155], v[192:195], v[96:99]
	v_mfma_f32_16x16x32_bf16 v[76:79], v[144:147], v[202:205], v[76:79]
	v_mfma_f32_16x16x32_bf16 v[68:71], v[152:155], v[202:205], v[68:71]
	v_mfma_f32_16x16x32_bf16 v[132:135], v[148:151], v[176:179], v[132:135]
	v_mfma_f32_16x16x32_bf16 v[128:131], v[156:159], v[176:179], v[128:131]
	v_mfma_f32_16x16x32_bf16 v[116:119], v[148:151], v[188:191], v[116:119]
	v_mfma_f32_16x16x32_bf16 v[112:115], v[156:159], v[188:191], v[112:115]
	v_mfma_f32_16x16x32_bf16 v[100:103], v[148:151], v[196:199], v[100:103]
	v_mfma_f32_16x16x32_bf16 v[96:99], v[156:159], v[196:199], v[96:99]
	v_mfma_f32_16x16x32_bf16 v[76:79], v[148:151], v[206:209], v[76:79]
	v_mfma_f32_16x16x32_bf16 v[68:71], v[156:159], v[206:209], v[68:71]
	s_barrier
	s_setprio 0
	ds_read_b128 v[172:175], v182 offset:16384
	ds_read_b128 v[176:179], v182 offset:17408
	ds_read_b128 v[184:187], v182 offset:18432
	ds_read_b128 v[188:191], v182 offset:19456
	ds_read_b128 v[192:195], v182 offset:20480
	ds_read_b128 v[196:199], v182 offset:21504
	ds_read_b128 v[202:205], v182 offset:22528
	ds_read_b128 v[206:209], v182 offset:23552
	s_add_i32 s67, s67, s41
	v_lshl_add_u64 v[212:213], s[30:31], 0, v[162:163]
	s_mov_b32 m0, s67
	s_nop 0
	global_load_lds_dwordx4 v[212:213], off
	s_add_i32 m0, s67, 0x2000
	s_add_u32 s68, s30, 0x80000
	v_lshl_add_u64 v[214:215], s[30:31], 0, v[166:167]
	s_addc_u32 s69, s31, 0
	s_add_i32 s67, s70, s41
	global_load_lds_dwordx4 v[214:215], off
	v_lshl_add_u64 v[216:217], s[68:69], 0, v[162:163]
	s_mov_b32 m0, s67
	v_lshl_add_u64 v[218:219], s[34:35], 0, v[164:165]
	global_load_lds_dwordx4 v[216:217], off
	v_lshl_add_u64 v[216:217], s[68:69], 0, v[166:167]
	s_add_i32 m0, s67, 0x2000
	s_nop 0
	global_load_lds_dwordx4 v[216:217], off
	v_lshl_add_u64 v[216:217], s[34:35], 0, v[160:161]
	s_mov_b32 m0, s27
	s_nop 0
	global_load_lds_dwordx4 v[216:217], off
	s_mov_b32 m0, s48
	s_nop 0
	global_load_lds_dwordx4 v[218:219], off
	s_waitcnt vmcnt(8)
	s_waitcnt lgkmcnt(0)
	s_setprio 1
	s_barrier
	v_mfma_f32_16x16x32_bf16 v[60:63], v[64:67], v[172:175], v[60:63]
	v_mfma_f32_16x16x32_bf16 v[56:59], v[80:83], v[172:175], v[56:59]
	v_mfma_f32_16x16x32_bf16 v[44:47], v[64:67], v[184:187], v[44:47]
	v_mfma_f32_16x16x32_bf16 v[40:43], v[80:83], v[184:187], v[40:43]
	v_mfma_f32_16x16x32_bf16 v[28:31], v[64:67], v[192:195], v[28:31]
	v_mfma_f32_16x16x32_bf16 v[24:27], v[80:83], v[192:195], v[24:27]
	v_mfma_f32_16x16x32_bf16 v[12:15], v[64:67], v[202:205], v[12:15]
	v_mfma_f32_16x16x32_bf16 v[8:11], v[80:83], v[202:205], v[8:11]
	v_mfma_f32_16x16x32_bf16 v[60:63], v[72:75], v[176:179], v[60:63]
	v_mfma_f32_16x16x32_bf16 v[56:59], v[84:87], v[176:179], v[56:59]
	v_mfma_f32_16x16x32_bf16 v[44:47], v[72:75], v[188:191], v[44:47]
	v_mfma_f32_16x16x32_bf16 v[40:43], v[84:87], v[188:191], v[40:43]
	v_mfma_f32_16x16x32_bf16 v[28:31], v[72:75], v[196:199], v[28:31]
	v_mfma_f32_16x16x32_bf16 v[24:27], v[84:87], v[196:199], v[24:27]
	v_mfma_f32_16x16x32_bf16 v[12:15], v[72:75], v[206:209], v[12:15]
	v_mfma_f32_16x16x32_bf16 v[8:11], v[84:87], v[206:209], v[8:11]
	s_setprio 0
	s_setprio 1
	v_mfma_f32_16x16x32_bf16 v[52:55], v[144:147], v[172:175], v[52:55]
	v_mfma_f32_16x16x32_bf16 v[48:51], v[152:155], v[172:175], v[48:51]
	v_mfma_f32_16x16x32_bf16 v[36:39], v[144:147], v[184:187], v[36:39]
	v_mfma_f32_16x16x32_bf16 v[32:35], v[152:155], v[184:187], v[32:35]
	v_mfma_f32_16x16x32_bf16 v[20:23], v[144:147], v[192:195], v[20:23]
	v_mfma_f32_16x16x32_bf16 v[16:19], v[152:155], v[192:195], v[16:19]
	v_mfma_f32_16x16x32_bf16 v[4:7], v[144:147], v[202:205], v[4:7]
	v_mfma_f32_16x16x32_bf16 v[0:3], v[152:155], v[202:205], v[0:3]
	v_mfma_f32_16x16x32_bf16 v[52:55], v[148:151], v[176:179], v[52:55]
	v_mfma_f32_16x16x32_bf16 v[48:51], v[156:159], v[176:179], v[48:51]
	v_mfma_f32_16x16x32_bf16 v[36:39], v[148:151], v[188:191], v[36:39]
	v_mfma_f32_16x16x32_bf16 v[32:35], v[156:159], v[188:191], v[32:35]
	v_mfma_f32_16x16x32_bf16 v[20:23], v[148:151], v[196:199], v[20:23]
	v_mfma_f32_16x16x32_bf16 v[16:19], v[156:159], v[196:199], v[16:19]
	v_mfma_f32_16x16x32_bf16 v[4:7], v[148:151], v[206:209], v[4:7]
	v_mfma_f32_16x16x32_bf16 v[0:3], v[156:159], v[206:209], v[0:3]
	s_barrier
	s_setprio 0
	ds_read_b128 v[64:67], v248
	ds_read_b128 v[72:75], v248 offset:1024
	ds_read_b128 v[80:83], v248 offset:2048
	ds_read_b128 v[84:87], v248 offset:3072
	ds_read_b128 v[144:147], v249
	ds_read_b128 v[148:151], v249 offset:1024
	ds_read_b128 v[152:155], v249 offset:2048
	ds_read_b128 v[156:159], v249 offset:3072
	ds_read_b128 v[172:175], v182 offset:32768
	ds_read_b128 v[176:179], v182 offset:33792
	ds_read_b128 v[184:187], v182 offset:34816
	ds_read_b128 v[188:191], v182 offset:35840
	ds_read_b128 v[192:195], v182 offset:36864
	ds_read_b128 v[196:199], v182 offset:37888
	ds_read_b128 v[202:205], v182 offset:38912
	ds_read_b128 v[206:209], v182 offset:39936
	s_add_i32 s67, 0, 0x18000
	s_add_i32 s68, 0, 0x1c000
	s_add_u32 s34, s34, 0x80000
	s_addc_u32 s35, s35, 0
	s_mov_b32 m0, s49
	v_lshl_add_u64 v[220:221], s[34:35], 0, v[160:161]
	global_load_lds_dwordx4 v[220:221], off
	v_lshl_add_u64 v[220:221], s[34:35], 0, v[164:165]
	s_mov_b32 m0, s50
	s_nop 0
	global_load_lds_dwordx4 v[220:221], off
	s_waitcnt vmcnt(8)
	s_waitcnt lgkmcnt(0)
	s_setprio 1
	s_barrier
	v_mfma_f32_16x16x32_bf16 v[140:143], v[64:67], v[172:175], v[140:143]
	v_mfma_f32_16x16x32_bf16 v[136:139], v[80:83], v[172:175], v[136:139]
	v_mfma_f32_16x16x32_bf16 v[124:127], v[64:67], v[184:187], v[124:127]
	v_mfma_f32_16x16x32_bf16 v[120:123], v[80:83], v[184:187], v[120:123]
	v_mfma_f32_16x16x32_bf16 v[108:111], v[64:67], v[192:195], v[108:111]
	v_mfma_f32_16x16x32_bf16 v[104:107], v[80:83], v[192:195], v[104:107]
	v_mfma_f32_16x16x32_bf16 v[92:95], v[64:67], v[202:205], v[92:95]
	v_mfma_f32_16x16x32_bf16 v[88:91], v[80:83], v[202:205], v[88:91]
	v_mfma_f32_16x16x32_bf16 v[140:143], v[72:75], v[176:179], v[140:143]
	v_mfma_f32_16x16x32_bf16 v[136:139], v[84:87], v[176:179], v[136:139]
	v_mfma_f32_16x16x32_bf16 v[124:127], v[72:75], v[188:191], v[124:127]
	v_mfma_f32_16x16x32_bf16 v[120:123], v[84:87], v[188:191], v[120:123]
	v_mfma_f32_16x16x32_bf16 v[108:111], v[72:75], v[196:199], v[108:111]
	v_mfma_f32_16x16x32_bf16 v[104:107], v[84:87], v[196:199], v[104:107]
	v_mfma_f32_16x16x32_bf16 v[92:95], v[72:75], v[206:209], v[92:95]
	v_mfma_f32_16x16x32_bf16 v[88:91], v[84:87], v[206:209], v[88:91]
	s_setprio 0
	s_setprio 1
	v_mfma_f32_16x16x32_bf16 v[132:135], v[144:147], v[172:175], v[132:135]
	v_mfma_f32_16x16x32_bf16 v[128:131], v[152:155], v[172:175], v[128:131]
	v_mfma_f32_16x16x32_bf16 v[116:119], v[144:147], v[184:187], v[116:119]
	v_mfma_f32_16x16x32_bf16 v[112:115], v[152:155], v[184:187], v[112:115]
	v_mfma_f32_16x16x32_bf16 v[100:103], v[144:147], v[192:195], v[100:103]
	v_mfma_f32_16x16x32_bf16 v[96:99], v[152:155], v[192:195], v[96:99]
	v_mfma_f32_16x16x32_bf16 v[76:79], v[144:147], v[202:205], v[76:79]
	v_mfma_f32_16x16x32_bf16 v[68:71], v[152:155], v[202:205], v[68:71]
	v_mfma_f32_16x16x32_bf16 v[132:135], v[148:151], v[176:179], v[132:135]
	v_mfma_f32_16x16x32_bf16 v[128:131], v[156:159], v[176:179], v[128:131]
	v_mfma_f32_16x16x32_bf16 v[116:119], v[148:151], v[188:191], v[116:119]
	v_mfma_f32_16x16x32_bf16 v[112:115], v[156:159], v[188:191], v[112:115]
	v_mfma_f32_16x16x32_bf16 v[100:103], v[148:151], v[196:199], v[100:103]
	v_mfma_f32_16x16x32_bf16 v[96:99], v[156:159], v[196:199], v[96:99]
	v_mfma_f32_16x16x32_bf16 v[76:79], v[148:151], v[206:209], v[76:79]
	v_mfma_f32_16x16x32_bf16 v[68:71], v[156:159], v[206:209], v[68:71]
	s_barrier
	s_setprio 0
	ds_read_b128 v[172:175], v182 offset:49152
	ds_read_b128 v[176:179], v182 offset:50176
	ds_read_b128 v[184:187], v182 offset:51200
	ds_read_b128 v[188:191], v182 offset:52224
	ds_read_b128 v[192:195], v182 offset:53248
	ds_read_b128 v[196:199], v182 offset:54272
	ds_read_b128 v[202:205], v182 offset:55296
	ds_read_b128 v[206:209], v182 offset:56320
	s_add_i32 s34, s67, s41
	v_lshl_add_u64 v[212:213], v[212:213], 0, s[64:65]
	s_mov_b32 m0, s34
	s_nop 0
	global_load_lds_dwordx4 v[212:213], off
	s_add_i32 m0, s34, 0x2000
	s_add_u32 s30, s30, 0x80080
	v_lshl_add_u64 v[212:213], v[214:215], 0, s[64:65]
	s_addc_u32 s31, s31, 0
	s_add_i32 s34, s68, s41
	global_load_lds_dwordx4 v[212:213], off
	v_lshl_add_u64 v[212:213], s[30:31], 0, v[162:163]
	s_mov_b32 m0, s34
	s_nop 0
	global_load_lds_dwordx4 v[212:213], off
	v_lshl_add_u64 v[212:213], s[30:31], 0, v[166:167]
	s_add_i32 m0, s34, 0x2000
	s_nop 0
	global_load_lds_dwordx4 v[212:213], off
	v_lshl_add_u64 v[212:213], v[216:217], 0, s[64:65]
	s_mov_b32 m0, s53
	s_nop 0
	global_load_lds_dwordx4 v[212:213], off
	v_lshl_add_u64 v[212:213], v[218:219], 0, s[64:65]
	s_mov_b32 m0, s56
	s_nop 0
	global_load_lds_dwordx4 v[212:213], off
	s_waitcnt vmcnt(8)
	s_waitcnt lgkmcnt(0)
	s_setprio 1
	s_barrier
	v_mfma_f32_16x16x32_bf16 v[60:63], v[64:67], v[172:175], v[60:63]
	v_mfma_f32_16x16x32_bf16 v[56:59], v[80:83], v[172:175], v[56:59]
	v_mfma_f32_16x16x32_bf16 v[44:47], v[64:67], v[184:187], v[44:47]
	v_mfma_f32_16x16x32_bf16 v[40:43], v[80:83], v[184:187], v[40:43]
	v_mfma_f32_16x16x32_bf16 v[28:31], v[64:67], v[192:195], v[28:31]
	v_mfma_f32_16x16x32_bf16 v[24:27], v[80:83], v[192:195], v[24:27]
	v_mfma_f32_16x16x32_bf16 v[12:15], v[64:67], v[202:205], v[12:15]
	v_mfma_f32_16x16x32_bf16 v[8:11], v[80:83], v[202:205], v[8:11]
	v_mfma_f32_16x16x32_bf16 v[60:63], v[72:75], v[176:179], v[60:63]
	v_mfma_f32_16x16x32_bf16 v[56:59], v[84:87], v[176:179], v[56:59]
	v_mfma_f32_16x16x32_bf16 v[44:47], v[72:75], v[188:191], v[44:47]
	v_mfma_f32_16x16x32_bf16 v[40:43], v[84:87], v[188:191], v[40:43]
	v_mfma_f32_16x16x32_bf16 v[28:31], v[72:75], v[196:199], v[28:31]
	v_mfma_f32_16x16x32_bf16 v[24:27], v[84:87], v[196:199], v[24:27]
	v_mfma_f32_16x16x32_bf16 v[12:15], v[72:75], v[206:209], v[12:15]
	v_mfma_f32_16x16x32_bf16 v[8:11], v[84:87], v[206:209], v[8:11]
	s_setprio 0
	s_setprio 1
	v_mfma_f32_16x16x32_bf16 v[52:55], v[144:147], v[172:175], v[52:55]
	v_mfma_f32_16x16x32_bf16 v[48:51], v[152:155], v[172:175], v[48:51]
	v_mfma_f32_16x16x32_bf16 v[36:39], v[144:147], v[184:187], v[36:39]
	v_mfma_f32_16x16x32_bf16 v[32:35], v[152:155], v[184:187], v[32:35]
	v_mfma_f32_16x16x32_bf16 v[20:23], v[144:147], v[192:195], v[20:23]
	v_mfma_f32_16x16x32_bf16 v[16:19], v[152:155], v[192:195], v[16:19]
	v_mfma_f32_16x16x32_bf16 v[4:7], v[144:147], v[202:205], v[4:7]
	v_mfma_f32_16x16x32_bf16 v[0:3], v[152:155], v[202:205], v[0:3]
	v_mfma_f32_16x16x32_bf16 v[52:55], v[148:151], v[176:179], v[52:55]
	v_mfma_f32_16x16x32_bf16 v[48:51], v[156:159], v[176:179], v[48:51]
	v_mfma_f32_16x16x32_bf16 v[36:39], v[148:151], v[188:191], v[36:39]
	v_mfma_f32_16x16x32_bf16 v[32:35], v[156:159], v[188:191], v[32:35]
	v_mfma_f32_16x16x32_bf16 v[20:23], v[148:151], v[196:199], v[20:23]
	v_mfma_f32_16x16x32_bf16 v[16:19], v[156:159], v[196:199], v[16:19]
	v_mfma_f32_16x16x32_bf16 v[4:7], v[148:151], v[206:209], v[4:7]
	v_mfma_f32_16x16x32_bf16 v[0:3], v[156:159], v[206:209], v[0:3]
	s_barrier
	s_setprio 0
	s_add_i32 s66, s66, 2
	s_add_u32 s28, s28, 0x100
	s_addc_u32 s29, s29, 0
	s_add_u32 s62, s62, 0x100
	s_addc_u32 s63, s63, 0
	s_cmp_gt_u32 s66, 29
	s_cbranch_scc0 .LBB0_189
	s_and_b64 vcc, exec, s[16:17]
	s_cbranch_vccz .LBB0_192
	s_barrier

.LBB0_642:
	s_ashr_i32 s23, s22, 31
	s_lshl_b64 s[8:9], s[22:23], 20
	s_add_u32 s24, s29, s8
	s_addc_u32 s25, s30, s9
	s_and_b64 s[8:9], s[2:3], exec
	s_cselect_b32 s1, s25, s5
	s_cselect_b32 s23, s24, s4
	s_ashr_i32 s21, s20, 31
	s_lshl_b64 s[8:9], s[20:21], 20
	s_add_u32 s26, s31, s8
	s_addc_u32 s27, s34, s9
	s_and_b64 s[8:9], s[2:3], exec
	s_cselect_b32 s21, s27, s7
	s_cselect_b32 s33, s26, s6
	s_add_u32 s4, s4, 0x80080
	s_addc_u32 s5, s5, 0
	s_add_u32 s42, s6, 0x100
	s_addc_u32 s43, s7, 0
	s_mov_b32 s49, -2
	v_mov_b32_e32 v0, v150
	v_mov_b32_e32 v1, v150
	s_waitcnt lgkmcnt(0)
	v_mov_b32_e32 v2, v150
	v_mov_b32_e32 v3, v150
	v_mov_b32_e32 v4, v150
	v_mov_b32_e32 v5, v150
	v_mov_b32_e32 v6, v150
	v_mov_b32_e32 v7, v150
	v_mov_b32_e32 v16, v150
	v_mov_b32_e32 v17, v150
	v_mov_b32_e32 v18, v150
	v_mov_b32_e32 v19, v150
	v_mov_b32_e32 v20, v150
	v_mov_b32_e32 v21, v150
	v_mov_b32_e32 v22, v150
	v_mov_b32_e32 v23, v150
	v_mov_b32_e32 v32, v150
	v_mov_b32_e32 v33, v150
	v_mov_b32_e32 v34, v150
	v_mov_b32_e32 v35, v150
	v_mov_b32_e32 v36, v150
	v_mov_b32_e32 v37, v150
	v_mov_b32_e32 v38, v150
	v_mov_b32_e32 v39, v150
	v_mov_b32_e32 v48, v150
	v_mov_b32_e32 v49, v150
	v_mov_b32_e32 v50, v150
	v_mov_b32_e32 v51, v150
	v_mov_b32_e32 v52, v150
	v_mov_b32_e32 v53, v150
	v_mov_b32_e32 v54, v150
	v_mov_b32_e32 v55, v150
	v_mov_b32_e32 v8, v150
	v_mov_b32_e32 v9, v150
	v_mov_b32_e32 v10, v150
	v_mov_b32_e32 v11, v150
	v_mov_b32_e32 v12, v150
	v_mov_b32_e32 v13, v150
	v_mov_b32_e32 v14, v150
	v_mov_b32_e32 v15, v150
	v_mov_b32_e32 v24, v150
	v_mov_b32_e32 v25, v150
	v_mov_b32_e32 v26, v150
	v_mov_b32_e32 v27, v150
	v_mov_b32_e32 v28, v150
	v_mov_b32_e32 v29, v150
	v_mov_b32_e32 v30, v150
	v_mov_b32_e32 v31, v150
	v_mov_b32_e32 v40, v150
	v_mov_b32_e32 v41, v150
	v_mov_b32_e32 v42, v150
	v_mov_b32_e32 v43, v150
	v_mov_b32_e32 v44, v150
	v_mov_b32_e32 v45, v150
	v_mov_b32_e32 v46, v150
	v_mov_b32_e32 v47, v150
	v_mov_b32_e32 v56, v150
	v_mov_b32_e32 v57, v150
	v_mov_b32_e32 v58, v150
	v_mov_b32_e32 v59, v150
	v_mov_b32_e32 v60, v150
	v_mov_b32_e32 v61, v150
	v_mov_b32_e32 v62, v150
	v_mov_b32_e32 v63, v150
	v_mov_b32_e32 v64, v150
	v_mov_b32_e32 v65, v150
	v_mov_b32_e32 v66, v150
	v_mov_b32_e32 v67, v150
	v_mov_b32_e32 v68, v150
	v_mov_b32_e32 v69, v150
	v_mov_b32_e32 v70, v150
	v_mov_b32_e32 v71, v150
	v_mov_b32_e32 v80, v150
	v_mov_b32_e32 v81, v150
	v_mov_b32_e32 v82, v150
	v_mov_b32_e32 v83, v150
	v_mov_b32_e32 v84, v150
	v_mov_b32_e32 v85, v150
	v_mov_b32_e32 v86, v150
	v_mov_b32_e32 v87, v150
	v_mov_b32_e32 v96, v150
	v_mov_b32_e32 v97, v150
	v_mov_b32_e32 v98, v150
	v_mov_b32_e32 v99, v150
	v_mov_b32_e32 v100, v150
	v_mov_b32_e32 v101, v150
	v_mov_b32_e32 v102, v150
	v_mov_b32_e32 v103, v150
	v_mov_b32_e32 v112, v150
	v_mov_b32_e32 v113, v150
	v_mov_b32_e32 v114, v150
	v_mov_b32_e32 v115, v150
	v_mov_b32_e32 v116, v150
	v_mov_b32_e32 v117, v150
	v_mov_b32_e32 v118, v150
	v_mov_b32_e32 v119, v150
	v_mov_b32_e32 v72, v150
	v_mov_b32_e32 v73, v150
	v_mov_b32_e32 v74, v150
	v_mov_b32_e32 v75, v150
	v_mov_b32_e32 v76, v150
	v_mov_b32_e32 v77, v150
	v_mov_b32_e32 v78, v150
	v_mov_b32_e32 v79, v150
	v_mov_b32_e32 v88, v150
	v_mov_b32_e32 v89, v150
	v_mov_b32_e32 v90, v150
	v_mov_b32_e32 v91, v150
	v_mov_b32_e32 v92, v150
	v_mov_b32_e32 v93, v150
	v_mov_b32_e32 v94, v150
	v_mov_b32_e32 v95, v150
	v_mov_b32_e32 v104, v150
	v_mov_b32_e32 v105, v150
	v_mov_b32_e32 v106, v150
	v_mov_b32_e32 v107, v150
	v_mov_b32_e32 v108, v150
	v_mov_b32_e32 v109, v150
	v_mov_b32_e32 v110, v150
	v_mov_b32_e32 v111, v150
	v_mov_b32_e32 v120, v150
	v_mov_b32_e32 v121, v150
	v_mov_b32_e32 v122, v150
	v_mov_b32_e32 v123, v150
	v_mov_b32_e32 v124, v150
	v_mov_b32_e32 v125, v150
	v_mov_b32_e32 v126, v150
	v_mov_b32_e32 v127, v150
	v_add_u32_e32 v246, 0x10000, v151
	v_add_u32_e32 v247, 0x14000, v151
	v_add_u32_e32 v248, 0x18000, v151
	v_add_u32_e32 v249, 0x1c000, v151
.LBB0_643:
	ds_read_b128 v[140:143], v246
	ds_read_b128 v[144:147], v246 offset:1024
	ds_read_b128 v[154:157], v246 offset:2048
	ds_read_b128 v[158:161], v246 offset:3072
	ds_read_b128 v[162:165], v247
	ds_read_b128 v[166:169], v247 offset:1024
	ds_read_b128 v[170:173], v247 offset:2048
	ds_read_b128 v[174:177], v247 offset:3072
	ds_read_b128 v[178:181], v152
	ds_read_b128 v[182:185], v152 offset:1024
	ds_read_b128 v[186:189], v152 offset:2048
	ds_read_b128 v[190:193], v152 offset:3072
	ds_read_b128 v[194:197], v152 offset:4096
	ds_read_b128 v[202:205], v152 offset:5120
	ds_read_b128 v[206:209], v152 offset:6144
	ds_read_b128 v[212:215], v152 offset:7168
	s_add_u32 s6, s4, 0xfff80080
	s_addc_u32 s7, s5, -1
	s_add_i32 s50, 0, 0x10000
	s_cmp_eq_u32 s49, 28
	s_cselect_b32 s9, s1, s7
	s_cselect_b32 s8, s23, s6
	s_cselect_b32 s7, s21, s43
	s_cselect_b32 s6, s33, s42
	s_add_i32 s53, 0, 0x14000
	v_lshl_add_u64 v[148:149], s[4:5], 0, v[136:137]
	s_add_i32 m0, s11, 0xc000
	s_nop 0
	global_load_lds_dwordx4 v[148:149], off
	v_lshl_add_u64 v[148:149], s[4:5], 0, v[138:139]
	s_add_i32 m0, s11, 0xe000
	s_nop 0
	global_load_lds_dwordx4 v[148:149], off
	s_waitcnt vmcnt(8)
	s_waitcnt lgkmcnt(0)
	s_setprio 1
	s_barrier
	v_mfma_f32_16x16x32_bf16 v[124:127], v[140:143], v[178:181], v[124:127]
	v_mfma_f32_16x16x32_bf16 v[120:123], v[154:157], v[178:181], v[120:123]
	v_mfma_f32_16x16x32_bf16 v[108:111], v[140:143], v[186:189], v[108:111]
	v_mfma_f32_16x16x32_bf16 v[104:107], v[154:157], v[186:189], v[104:107]
	v_mfma_f32_16x16x32_bf16 v[92:95], v[140:143], v[194:197], v[92:95]
	v_mfma_f32_16x16x32_bf16 v[88:91], v[154:157], v[194:197], v[88:91]
	v_mfma_f32_16x16x32_bf16 v[76:79], v[140:143], v[206:209], v[76:79]
	v_mfma_f32_16x16x32_bf16 v[72:75], v[154:157], v[206:209], v[72:75]
	v_mfma_f32_16x16x32_bf16 v[124:127], v[144:147], v[182:185], v[124:127]
	v_mfma_f32_16x16x32_bf16 v[120:123], v[158:161], v[182:185], v[120:123]
	v_mfma_f32_16x16x32_bf16 v[108:111], v[144:147], v[190:193], v[108:111]
	v_mfma_f32_16x16x32_bf16 v[104:107], v[158:161], v[190:193], v[104:107]
	v_mfma_f32_16x16x32_bf16 v[92:95], v[144:147], v[202:205], v[92:95]
	v_mfma_f32_16x16x32_bf16 v[88:91], v[158:161], v[202:205], v[88:91]
	v_mfma_f32_16x16x32_bf16 v[76:79], v[144:147], v[212:215], v[76:79]
	v_mfma_f32_16x16x32_bf16 v[72:75], v[158:161], v[212:215], v[72:75]
	s_setprio 0
	s_setprio 1
	v_mfma_f32_16x16x32_bf16 v[116:119], v[162:165], v[178:181], v[116:119]
	v_mfma_f32_16x16x32_bf16 v[112:115], v[170:173], v[178:181], v[112:115]
	v_mfma_f32_16x16x32_bf16 v[100:103], v[162:165], v[186:189], v[100:103]
	v_mfma_f32_16x16x32_bf16 v[96:99], v[170:173], v[186:189], v[96:99]
	v_mfma_f32_16x16x32_bf16 v[84:87], v[162:165], v[194:197], v[84:87]
	v_mfma_f32_16x16x32_bf16 v[80:83], v[170:173], v[194:197], v[80:83]
	v_mfma_f32_16x16x32_bf16 v[68:71], v[162:165], v[206:209], v[68:71]
	v_mfma_f32_16x16x32_bf16 v[64:67], v[170:173], v[206:209], v[64:67]
	v_mfma_f32_16x16x32_bf16 v[116:119], v[166:169], v[182:185], v[116:119]
	v_mfma_f32_16x16x32_bf16 v[112:115], v[174:177], v[182:185], v[112:115]
	v_mfma_f32_16x16x32_bf16 v[100:103], v[166:169], v[190:193], v[100:103]
	v_mfma_f32_16x16x32_bf16 v[96:99], v[174:177], v[190:193], v[96:99]
	v_mfma_f32_16x16x32_bf16 v[84:87], v[166:169], v[202:205], v[84:87]
	v_mfma_f32_16x16x32_bf16 v[80:83], v[174:177], v[202:205], v[80:83]
	v_mfma_f32_16x16x32_bf16 v[68:71], v[166:169], v[212:215], v[68:71]
	v_mfma_f32_16x16x32_bf16 v[64:67], v[174:177], v[212:215], v[64:67]
	s_barrier
	s_setprio 0
	ds_read_b128 v[178:181], v152 offset:16384
	ds_read_b128 v[182:185], v152 offset:17408
	ds_read_b128 v[186:189], v152 offset:18432
	ds_read_b128 v[190:193], v152 offset:19456
	ds_read_b128 v[194:197], v152 offset:20480
	ds_read_b128 v[202:205], v152 offset:21504
	ds_read_b128 v[206:209], v152 offset:22528
	ds_read_b128 v[212:215], v152 offset:23552
	s_add_i32 s50, s50, s35
	v_lshl_add_u64 v[148:149], s[6:7], 0, v[130:131]
	s_mov_b32 m0, s50
	s_nop 0
	global_load_lds_dwordx4 v[148:149], off
	s_add_i32 m0, s50, 0x2000
	s_add_u32 s50, s6, 0x80000
	v_lshl_add_u64 v[198:199], s[6:7], 0, v[134:135]
	s_addc_u32 s51, s7, 0
	s_add_i32 s53, s53, s35
	global_load_lds_dwordx4 v[198:199], off
	v_lshl_add_u64 v[216:217], s[50:51], 0, v[130:131]
	s_mov_b32 m0, s53
	v_lshl_add_u64 v[218:219], s[8:9], 0, v[132:133]
	global_load_lds_dwordx4 v[216:217], off
	v_lshl_add_u64 v[216:217], s[50:51], 0, v[134:135]
	s_add_i32 m0, s53, 0x2000
	s_nop 0
	global_load_lds_dwordx4 v[216:217], off
	v_lshl_add_u64 v[216:217], s[8:9], 0, v[128:129]
	s_mov_b32 m0, s11
	s_nop 0
	global_load_lds_dwordx4 v[216:217], off
	s_mov_b32 m0, s36
	s_nop 0
	global_load_lds_dwordx4 v[218:219], off
	s_waitcnt vmcnt(8)
	s_waitcnt lgkmcnt(0)
	s_setprio 1
	s_barrier
	v_mfma_f32_16x16x32_bf16 v[60:63], v[140:143], v[178:181], v[60:63]
	v_mfma_f32_16x16x32_bf16 v[56:59], v[154:157], v[178:181], v[56:59]
	v_mfma_f32_16x16x32_bf16 v[44:47], v[140:143], v[186:189], v[44:47]
	v_mfma_f32_16x16x32_bf16 v[40:43], v[154:157], v[186:189], v[40:43]
	v_mfma_f32_16x16x32_bf16 v[28:31], v[140:143], v[194:197], v[28:31]
	v_mfma_f32_16x16x32_bf16 v[24:27], v[154:157], v[194:197], v[24:27]
	v_mfma_f32_16x16x32_bf16 v[12:15], v[140:143], v[206:209], v[12:15]
	v_mfma_f32_16x16x32_bf16 v[8:11], v[154:157], v[206:209], v[8:11]
	v_mfma_f32_16x16x32_bf16 v[60:63], v[144:147], v[182:185], v[60:63]
	v_mfma_f32_16x16x32_bf16 v[56:59], v[158:161], v[182:185], v[56:59]
	v_mfma_f32_16x16x32_bf16 v[44:47], v[144:147], v[190:193], v[44:47]
	v_mfma_f32_16x16x32_bf16 v[40:43], v[158:161], v[190:193], v[40:43]
	v_mfma_f32_16x16x32_bf16 v[28:31], v[144:147], v[202:205], v[28:31]
	v_mfma_f32_16x16x32_bf16 v[24:27], v[158:161], v[202:205], v[24:27]
	v_mfma_f32_16x16x32_bf16 v[12:15], v[144:147], v[212:215], v[12:15]
	v_mfma_f32_16x16x32_bf16 v[8:11], v[158:161], v[212:215], v[8:11]
	s_setprio 0
	s_setprio 1
	v_mfma_f32_16x16x32_bf16 v[52:55], v[162:165], v[178:181], v[52:55]
	v_mfma_f32_16x16x32_bf16 v[48:51], v[170:173], v[178:181], v[48:51]
	v_mfma_f32_16x16x32_bf16 v[36:39], v[162:165], v[186:189], v[36:39]
	v_mfma_f32_16x16x32_bf16 v[32:35], v[170:173], v[186:189], v[32:35]
	v_mfma_f32_16x16x32_bf16 v[20:23], v[162:165], v[194:197], v[20:23]
	v_mfma_f32_16x16x32_bf16 v[16:19], v[170:173], v[194:197], v[16:19]
	v_mfma_f32_16x16x32_bf16 v[4:7], v[162:165], v[206:209], v[4:7]
	v_mfma_f32_16x16x32_bf16 v[0:3], v[170:173], v[206:209], v[0:3]
	v_mfma_f32_16x16x32_bf16 v[52:55], v[166:169], v[182:185], v[52:55]
	v_mfma_f32_16x16x32_bf16 v[48:51], v[174:177], v[182:185], v[48:51]
	v_mfma_f32_16x16x32_bf16 v[36:39], v[166:169], v[190:193], v[36:39]
	v_mfma_f32_16x16x32_bf16 v[32:35], v[174:177], v[190:193], v[32:35]
	v_mfma_f32_16x16x32_bf16 v[20:23], v[166:169], v[202:205], v[20:23]
	v_mfma_f32_16x16x32_bf16 v[16:19], v[174:177], v[202:205], v[16:19]
	v_mfma_f32_16x16x32_bf16 v[4:7], v[166:169], v[212:215], v[4:7]
	v_mfma_f32_16x16x32_bf16 v[0:3], v[174:177], v[212:215], v[0:3]
	s_barrier
	s_setprio 0
	ds_read_b128 v[140:143], v248
	ds_read_b128 v[144:147], v248 offset:1024
	ds_read_b128 v[154:157], v248 offset:2048
	ds_read_b128 v[158:161], v248 offset:3072
	ds_read_b128 v[162:165], v249
	ds_read_b128 v[166:169], v249 offset:1024
	ds_read_b128 v[170:173], v249 offset:2048
	ds_read_b128 v[174:177], v249 offset:3072
	ds_read_b128 v[178:181], v152 offset:32768
	ds_read_b128 v[182:185], v152 offset:33792
	ds_read_b128 v[186:189], v152 offset:34816
	ds_read_b128 v[190:193], v152 offset:35840
	ds_read_b128 v[194:197], v152 offset:36864
	ds_read_b128 v[202:205], v152 offset:37888
	ds_read_b128 v[206:209], v152 offset:38912
	ds_read_b128 v[212:215], v152 offset:39936
	s_add_i32 s50, 0, 0x18000
	s_add_i32 s51, 0, 0x1c000
	s_add_u32 s8, s8, 0x80000
	s_addc_u32 s9, s9, 0
	s_mov_b32 m0, s37
	v_lshl_add_u64 v[220:221], s[8:9], 0, v[128:129]
	global_load_lds_dwordx4 v[220:221], off
	v_lshl_add_u64 v[220:221], s[8:9], 0, v[132:133]
	s_mov_b32 m0, s38
	s_nop 0
	global_load_lds_dwordx4 v[220:221], off
	s_waitcnt vmcnt(8)
	s_waitcnt lgkmcnt(0)
	s_setprio 1
	s_barrier
	v_mfma_f32_16x16x32_bf16 v[124:127], v[140:143], v[178:181], v[124:127]
	v_mfma_f32_16x16x32_bf16 v[120:123], v[154:157], v[178:181], v[120:123]
	v_mfma_f32_16x16x32_bf16 v[108:111], v[140:143], v[186:189], v[108:111]
	v_mfma_f32_16x16x32_bf16 v[104:107], v[154:157], v[186:189], v[104:107]
	v_mfma_f32_16x16x32_bf16 v[92:95], v[140:143], v[194:197], v[92:95]
	v_mfma_f32_16x16x32_bf16 v[88:91], v[154:157], v[194:197], v[88:91]
	v_mfma_f32_16x16x32_bf16 v[76:79], v[140:143], v[206:209], v[76:79]
	v_mfma_f32_16x16x32_bf16 v[72:75], v[154:157], v[206:209], v[72:75]
	v_mfma_f32_16x16x32_bf16 v[124:127], v[144:147], v[182:185], v[124:127]
	v_mfma_f32_16x16x32_bf16 v[120:123], v[158:161], v[182:185], v[120:123]
	v_mfma_f32_16x16x32_bf16 v[108:111], v[144:147], v[190:193], v[108:111]
	v_mfma_f32_16x16x32_bf16 v[104:107], v[158:161], v[190:193], v[104:107]
	v_mfma_f32_16x16x32_bf16 v[92:95], v[144:147], v[202:205], v[92:95]
	v_mfma_f32_16x16x32_bf16 v[88:91], v[158:161], v[202:205], v[88:91]
	v_mfma_f32_16x16x32_bf16 v[76:79], v[144:147], v[212:215], v[76:79]
	v_mfma_f32_16x16x32_bf16 v[72:75], v[158:161], v[212:215], v[72:75]
	s_setprio 0
	s_setprio 1
	v_mfma_f32_16x16x32_bf16 v[116:119], v[162:165], v[178:181], v[116:119]
	v_mfma_f32_16x16x32_bf16 v[112:115], v[170:173], v[178:181], v[112:115]
	v_mfma_f32_16x16x32_bf16 v[100:103], v[162:165], v[186:189], v[100:103]
	v_mfma_f32_16x16x32_bf16 v[96:99], v[170:173], v[186:189], v[96:99]
	v_mfma_f32_16x16x32_bf16 v[84:87], v[162:165], v[194:197], v[84:87]
	v_mfma_f32_16x16x32_bf16 v[80:83], v[170:173], v[194:197], v[80:83]
	v_mfma_f32_16x16x32_bf16 v[68:71], v[162:165], v[206:209], v[68:71]
	v_mfma_f32_16x16x32_bf16 v[64:67], v[170:173], v[206:209], v[64:67]
	v_mfma_f32_16x16x32_bf16 v[116:119], v[166:169], v[182:185], v[116:119]
	v_mfma_f32_16x16x32_bf16 v[112:115], v[174:177], v[182:185], v[112:115]
	v_mfma_f32_16x16x32_bf16 v[100:103], v[166:169], v[190:193], v[100:103]
	v_mfma_f32_16x16x32_bf16 v[96:99], v[174:177], v[190:193], v[96:99]
	v_mfma_f32_16x16x32_bf16 v[84:87], v[166:169], v[202:205], v[84:87]
	v_mfma_f32_16x16x32_bf16 v[80:83], v[174:177], v[202:205], v[80:83]
	v_mfma_f32_16x16x32_bf16 v[68:71], v[166:169], v[212:215], v[68:71]
	v_mfma_f32_16x16x32_bf16 v[64:67], v[174:177], v[212:215], v[64:67]
	s_barrier
	s_setprio 0
	ds_read_b128 v[178:181], v152 offset:49152
	ds_read_b128 v[182:185], v152 offset:50176
	ds_read_b128 v[186:189], v152 offset:51200
	ds_read_b128 v[190:193], v152 offset:52224
	ds_read_b128 v[194:197], v152 offset:53248
	ds_read_b128 v[202:205], v152 offset:54272
	ds_read_b128 v[206:209], v152 offset:55296
	ds_read_b128 v[212:215], v152 offset:56320
	s_add_i32 s8, s50, s35
	v_lshl_add_u64 v[148:149], v[148:149], 0, s[64:65]
	s_mov_b32 m0, s8
	s_nop 0
	global_load_lds_dwordx4 v[148:149], off
	s_add_i32 m0, s8, 0x2000
	s_add_u32 s6, s6, 0x80080
	v_lshl_add_u64 v[148:149], v[198:199], 0, s[64:65]
	s_addc_u32 s7, s7, 0
	s_add_i32 s8, s51, s35
	global_load_lds_dwordx4 v[148:149], off
	v_lshl_add_u64 v[148:149], s[6:7], 0, v[130:131]
	s_mov_b32 m0, s8
	s_nop 0
	global_load_lds_dwordx4 v[148:149], off
	v_lshl_add_u64 v[148:149], s[6:7], 0, v[134:135]
	s_add_i32 m0, s8, 0x2000
	s_nop 0
	global_load_lds_dwordx4 v[148:149], off
	v_lshl_add_u64 v[148:149], v[216:217], 0, s[64:65]
	s_mov_b32 m0, s40
	s_nop 0
	global_load_lds_dwordx4 v[148:149], off
	v_lshl_add_u64 v[148:149], v[218:219], 0, s[64:65]
	s_mov_b32 m0, s41
	s_nop 0
	global_load_lds_dwordx4 v[148:149], off
	s_waitcnt vmcnt(8)
	s_waitcnt lgkmcnt(0)
	s_setprio 1
	s_barrier
	v_mfma_f32_16x16x32_bf16 v[60:63], v[140:143], v[178:181], v[60:63]
	v_mfma_f32_16x16x32_bf16 v[56:59], v[154:157], v[178:181], v[56:59]
	v_mfma_f32_16x16x32_bf16 v[44:47], v[140:143], v[186:189], v[44:47]
	v_mfma_f32_16x16x32_bf16 v[40:43], v[154:157], v[186:189], v[40:43]
	v_mfma_f32_16x16x32_bf16 v[28:31], v[140:143], v[194:197], v[28:31]
	v_mfma_f32_16x16x32_bf16 v[24:27], v[154:157], v[194:197], v[24:27]
	v_mfma_f32_16x16x32_bf16 v[12:15], v[140:143], v[206:209], v[12:15]
	v_mfma_f32_16x16x32_bf16 v[8:11], v[154:157], v[206:209], v[8:11]
	v_mfma_f32_16x16x32_bf16 v[60:63], v[144:147], v[182:185], v[60:63]
	v_mfma_f32_16x16x32_bf16 v[56:59], v[158:161], v[182:185], v[56:59]
	v_mfma_f32_16x16x32_bf16 v[44:47], v[144:147], v[190:193], v[44:47]
	v_mfma_f32_16x16x32_bf16 v[40:43], v[158:161], v[190:193], v[40:43]
	v_mfma_f32_16x16x32_bf16 v[28:31], v[144:147], v[202:205], v[28:31]
	v_mfma_f32_16x16x32_bf16 v[24:27], v[158:161], v[202:205], v[24:27]
	v_mfma_f32_16x16x32_bf16 v[12:15], v[144:147], v[212:215], v[12:15]
	v_mfma_f32_16x16x32_bf16 v[8:11], v[158:161], v[212:215], v[8:11]
	s_setprio 0
	s_setprio 1
	v_mfma_f32_16x16x32_bf16 v[52:55], v[162:165], v[178:181], v[52:55]
	v_mfma_f32_16x16x32_bf16 v[48:51], v[170:173], v[178:181], v[48:51]
	v_mfma_f32_16x16x32_bf16 v[36:39], v[162:165], v[186:189], v[36:39]
	v_mfma_f32_16x16x32_bf16 v[32:35], v[170:173], v[186:189], v[32:35]
	v_mfma_f32_16x16x32_bf16 v[20:23], v[162:165], v[194:197], v[20:23]
	v_mfma_f32_16x16x32_bf16 v[16:19], v[170:173], v[194:197], v[16:19]
	v_mfma_f32_16x16x32_bf16 v[4:7], v[162:165], v[206:209], v[4:7]
	v_mfma_f32_16x16x32_bf16 v[0:3], v[170:173], v[206:209], v[0:3]
	v_mfma_f32_16x16x32_bf16 v[52:55], v[166:169], v[182:185], v[52:55]
	v_mfma_f32_16x16x32_bf16 v[48:51], v[174:177], v[182:185], v[48:51]
	v_mfma_f32_16x16x32_bf16 v[36:39], v[166:169], v[190:193], v[36:39]
	v_mfma_f32_16x16x32_bf16 v[32:35], v[174:177], v[190:193], v[32:35]
	v_mfma_f32_16x16x32_bf16 v[20:23], v[166:169], v[202:205], v[20:23]
	v_mfma_f32_16x16x32_bf16 v[16:19], v[174:177], v[202:205], v[16:19]
	v_mfma_f32_16x16x32_bf16 v[4:7], v[166:169], v[212:215], v[4:7]
	v_mfma_f32_16x16x32_bf16 v[0:3], v[174:177], v[212:215], v[0:3]
	s_barrier
	s_setprio 0
	s_add_i32 s49, s49, 2
	s_add_u32 s4, s4, 0x100
	s_addc_u32 s5, s5, 0
	s_add_u32 s42, s42, 0x100
	s_addc_u32 s43, s43, 0
	s_cmp_gt_u32 s49, 29
	s_cbranch_scc0 .LBB0_643
	s_and_b64 vcc, exec, s[18:19]
	s_cbranch_vccz .LBB0_646
	s_barrier

.LBB0_973:
	s_add_u32 s4, s70, 0x80
	s_addc_u32 s5, s71, 0
	s_add_u32 s70, s68, 0x100
	s_addc_u32 s71, s69, 0
	s_mov_b32 s68, 0
	v_mov_b32_e32 v0, v180
	v_mov_b32_e32 v1, v180
	s_waitcnt lgkmcnt(0)
	v_mov_b32_e32 v2, v180
	v_mov_b32_e32 v3, v180
	v_mov_b32_e32 v4, v180
	v_mov_b32_e32 v5, v180
	v_mov_b32_e32 v6, v180
	v_mov_b32_e32 v7, v180
	v_mov_b32_e32 v8, v180
	v_mov_b32_e32 v9, v180
	v_mov_b32_e32 v10, v180
	v_mov_b32_e32 v11, v180
	v_mov_b32_e32 v12, v180
	v_mov_b32_e32 v13, v180
	v_mov_b32_e32 v14, v180
	v_mov_b32_e32 v15, v180
	v_mov_b32_e32 v16, v180
	v_mov_b32_e32 v17, v180
	v_mov_b32_e32 v18, v180
	v_mov_b32_e32 v19, v180
	v_mov_b32_e32 v20, v180
	v_mov_b32_e32 v21, v180
	v_mov_b32_e32 v22, v180
	v_mov_b32_e32 v23, v180
	v_mov_b32_e32 v24, v180
	v_mov_b32_e32 v25, v180
	v_mov_b32_e32 v26, v180
	v_mov_b32_e32 v27, v180
	v_mov_b32_e32 v28, v180
	v_mov_b32_e32 v29, v180
	v_mov_b32_e32 v30, v180
	v_mov_b32_e32 v31, v180
	v_mov_b32_e32 v32, v180
	v_mov_b32_e32 v33, v180
	v_mov_b32_e32 v34, v180
	v_mov_b32_e32 v35, v180
	v_mov_b32_e32 v36, v180
	v_mov_b32_e32 v37, v180
	v_mov_b32_e32 v38, v180
	v_mov_b32_e32 v39, v180
	v_mov_b32_e32 v40, v180
	v_mov_b32_e32 v41, v180
	v_mov_b32_e32 v42, v180
	v_mov_b32_e32 v43, v180
	v_mov_b32_e32 v44, v180
	v_mov_b32_e32 v45, v180
	v_mov_b32_e32 v46, v180
	v_mov_b32_e32 v47, v180
	v_mov_b32_e32 v48, v180
	v_mov_b32_e32 v49, v180
	v_mov_b32_e32 v50, v180
	v_mov_b32_e32 v51, v180
	v_mov_b32_e32 v52, v180
	v_mov_b32_e32 v53, v180
	v_mov_b32_e32 v54, v180
	v_mov_b32_e32 v55, v180
	v_mov_b32_e32 v56, v180
	v_mov_b32_e32 v57, v180
	v_mov_b32_e32 v58, v180
	v_mov_b32_e32 v59, v180
	v_mov_b32_e32 v60, v180
	v_mov_b32_e32 v61, v180
	v_mov_b32_e32 v62, v180
	v_mov_b32_e32 v63, v180
	v_mov_b32_e32 v64, v180
	v_mov_b32_e32 v65, v180
	v_mov_b32_e32 v66, v180
	v_mov_b32_e32 v67, v180
	v_mov_b32_e32 v68, v180
	v_mov_b32_e32 v69, v180
	v_mov_b32_e32 v70, v180
	v_mov_b32_e32 v71, v180
	v_mov_b32_e32 v72, v180
	v_mov_b32_e32 v73, v180
	v_mov_b32_e32 v74, v180
	v_mov_b32_e32 v75, v180
	v_mov_b32_e32 v76, v180
	v_mov_b32_e32 v77, v180
	v_mov_b32_e32 v78, v180
	v_mov_b32_e32 v79, v180
	v_mov_b32_e32 v80, v180
	v_mov_b32_e32 v81, v180
	v_mov_b32_e32 v82, v180
	v_mov_b32_e32 v83, v180
	v_mov_b32_e32 v84, v180
	v_mov_b32_e32 v85, v180
	v_mov_b32_e32 v86, v180
	v_mov_b32_e32 v87, v180
	v_mov_b32_e32 v88, v180
	v_mov_b32_e32 v89, v180
	v_mov_b32_e32 v90, v180
	v_mov_b32_e32 v91, v180
	v_mov_b32_e32 v92, v180
	v_mov_b32_e32 v93, v180
	v_mov_b32_e32 v94, v180
	v_mov_b32_e32 v95, v180
	v_mov_b32_e32 v96, v180
	v_mov_b32_e32 v97, v180
	v_mov_b32_e32 v98, v180
	v_mov_b32_e32 v99, v180
	v_mov_b32_e32 v100, v180
	v_mov_b32_e32 v101, v180
	v_mov_b32_e32 v102, v180
	v_mov_b32_e32 v103, v180
	v_mov_b32_e32 v104, v180
	v_mov_b32_e32 v105, v180
	v_mov_b32_e32 v106, v180
	v_mov_b32_e32 v107, v180
	v_mov_b32_e32 v108, v180
	v_mov_b32_e32 v109, v180
	v_mov_b32_e32 v110, v180
	v_mov_b32_e32 v111, v180
	v_mov_b32_e32 v112, v180
	v_mov_b32_e32 v113, v180
	v_mov_b32_e32 v114, v180
	v_mov_b32_e32 v115, v180
	v_mov_b32_e32 v116, v180
	v_mov_b32_e32 v117, v180
	v_mov_b32_e32 v118, v180
	v_mov_b32_e32 v119, v180
	v_mov_b32_e32 v120, v180
	v_mov_b32_e32 v121, v180
	v_mov_b32_e32 v122, v180
	v_mov_b32_e32 v123, v180
	v_mov_b32_e32 v124, v180
	v_mov_b32_e32 v125, v180
	v_mov_b32_e32 v126, v180
	v_mov_b32_e32 v127, v180
	v_add_u32_e32 v246, 0x10000, v181
	v_add_u32_e32 v247, 0x14000, v181
	v_add_u32_e32 v248, 0x18000, v181
	v_add_u32_e32 v249, 0x1c000, v181
.LBB0_974:
	ds_read_b128 v[128:131], v246
	ds_read_b128 v[132:135], v246 offset:1024
	ds_read_b128 v[136:139], v246 offset:2048
	ds_read_b128 v[152:155], v246 offset:3072
	ds_read_b128 v[156:159], v247
	ds_read_b128 v[160:163], v247 offset:1024
	ds_read_b128 v[164:167], v247 offset:2048
	ds_read_b128 v[168:171], v247 offset:3072
	ds_read_b128 v[172:175], v182
	ds_read_b128 v[176:179], v182 offset:1024
	ds_read_b128 v[184:187], v182 offset:2048
	ds_read_b128 v[188:191], v182 offset:3072
	ds_read_b128 v[192:195], v182 offset:4096
	ds_read_b128 v[196:199], v182 offset:5120
	ds_read_b128 v[202:205], v182 offset:6144
	ds_read_b128 v[206:209], v182 offset:7168
	s_add_i32 s88, s68, 2
	s_add_u32 s89, s4, 0x80
	s_addc_u32 s69, s5, 0
	s_add_i32 s92, 0, 0x10000
	s_cmp_eq_u32 s84, s68
	s_cselect_b32 s69, s63, s69
	s_cselect_b32 s68, s62, s89
	s_cselect_b32 s91, s67, s71
	s_cselect_b32 s90, s66, s70
	s_add_i32 s89, 0, 0x14000
	v_lshl_add_u64 v[212:213], s[4:5], 0, v[148:149]
	s_add_i32 m0, s76, 0xc000
	s_nop 0
	global_load_lds_dwordx4 v[212:213], off
	v_lshl_add_u64 v[212:213], s[4:5], 0, v[150:151]
	s_add_i32 m0, s76, 0xe000
	s_nop 0
	global_load_lds_dwordx4 v[212:213], off
	s_waitcnt vmcnt(8)
	s_waitcnt lgkmcnt(0)
	s_setprio 1
	s_barrier
	v_mfma_f32_16x16x32_bf16 v[124:127], v[128:131], v[172:175], v[124:127]
	v_mfma_f32_16x16x32_bf16 v[120:123], v[136:139], v[172:175], v[120:123]
	v_mfma_f32_16x16x32_bf16 v[116:119], v[128:131], v[184:187], v[116:119]
	v_mfma_f32_16x16x32_bf16 v[112:115], v[136:139], v[184:187], v[112:115]
	v_mfma_f32_16x16x32_bf16 v[108:111], v[128:131], v[192:195], v[108:111]
	v_mfma_f32_16x16x32_bf16 v[104:107], v[136:139], v[192:195], v[104:107]
	v_mfma_f32_16x16x32_bf16 v[100:103], v[128:131], v[202:205], v[100:103]
	v_mfma_f32_16x16x32_bf16 v[96:99], v[136:139], v[202:205], v[96:99]
	v_mfma_f32_16x16x32_bf16 v[124:127], v[132:135], v[176:179], v[124:127]
	v_mfma_f32_16x16x32_bf16 v[120:123], v[152:155], v[176:179], v[120:123]
	v_mfma_f32_16x16x32_bf16 v[116:119], v[132:135], v[188:191], v[116:119]
	v_mfma_f32_16x16x32_bf16 v[112:115], v[152:155], v[188:191], v[112:115]
	v_mfma_f32_16x16x32_bf16 v[108:111], v[132:135], v[196:199], v[108:111]
	v_mfma_f32_16x16x32_bf16 v[104:107], v[152:155], v[196:199], v[104:107]
	v_mfma_f32_16x16x32_bf16 v[100:103], v[132:135], v[206:209], v[100:103]
	v_mfma_f32_16x16x32_bf16 v[96:99], v[152:155], v[206:209], v[96:99]
	s_setprio 0
	s_setprio 1
	v_mfma_f32_16x16x32_bf16 v[92:95], v[156:159], v[172:175], v[92:95]
	v_mfma_f32_16x16x32_bf16 v[88:91], v[164:167], v[172:175], v[88:91]
	v_mfma_f32_16x16x32_bf16 v[84:87], v[156:159], v[184:187], v[84:87]
	v_mfma_f32_16x16x32_bf16 v[80:83], v[164:167], v[184:187], v[80:83]
	v_mfma_f32_16x16x32_bf16 v[76:79], v[156:159], v[192:195], v[76:79]
	v_mfma_f32_16x16x32_bf16 v[72:75], v[164:167], v[192:195], v[72:75]
	v_mfma_f32_16x16x32_bf16 v[68:71], v[156:159], v[202:205], v[68:71]
	v_mfma_f32_16x16x32_bf16 v[64:67], v[164:167], v[202:205], v[64:67]
	v_mfma_f32_16x16x32_bf16 v[92:95], v[160:163], v[176:179], v[92:95]
	v_mfma_f32_16x16x32_bf16 v[88:91], v[168:171], v[176:179], v[88:91]
	v_mfma_f32_16x16x32_bf16 v[84:87], v[160:163], v[188:191], v[84:87]
	v_mfma_f32_16x16x32_bf16 v[80:83], v[168:171], v[188:191], v[80:83]
	v_mfma_f32_16x16x32_bf16 v[76:79], v[160:163], v[196:199], v[76:79]
	v_mfma_f32_16x16x32_bf16 v[72:75], v[168:171], v[196:199], v[72:75]
	v_mfma_f32_16x16x32_bf16 v[68:71], v[160:163], v[206:209], v[68:71]
	v_mfma_f32_16x16x32_bf16 v[64:67], v[168:171], v[206:209], v[64:67]
	s_barrier
	s_setprio 0
	ds_read_b128 v[172:175], v182 offset:16384
	ds_read_b128 v[176:179], v182 offset:17408
	ds_read_b128 v[184:187], v182 offset:18432
	ds_read_b128 v[188:191], v182 offset:19456
	ds_read_b128 v[192:195], v182 offset:20480
	ds_read_b128 v[196:199], v182 offset:21504
	ds_read_b128 v[202:205], v182 offset:22528
	ds_read_b128 v[206:209], v182 offset:23552
	s_add_i32 s92, s92, s72
	v_lshl_add_u64 v[212:213], s[90:91], 0, v[142:143]
	s_mov_b32 m0, s92
	s_nop 0
	global_load_lds_dwordx4 v[212:213], off
	s_add_i32 m0, s92, 0x2000
	v_lshl_add_u64 v[214:215], s[90:91], 0, v[146:147]
	s_add_u32 s90, s90, s56
	s_addc_u32 s91, s91, 0
	s_add_i32 s89, s89, s72
	global_load_lds_dwordx4 v[214:215], off
	v_lshl_add_u64 v[216:217], s[90:91], 0, v[142:143]
	s_mov_b32 m0, s89
	v_lshl_add_u64 v[218:219], s[90:91], 0, v[146:147]
	global_load_lds_dwordx4 v[216:217], off
	s_add_i32 m0, s89, 0x2000
	v_lshl_add_u64 v[220:221], s[68:69], 0, v[140:141]
	global_load_lds_dwordx4 v[218:219], off
	s_mov_b32 m0, s76
	v_lshl_add_u64 v[222:223], s[68:69], 0, v[144:145]
	global_load_lds_dwordx4 v[220:221], off
	s_mov_b32 m0, s77
	s_nop 0
	global_load_lds_dwordx4 v[222:223], off
	s_waitcnt vmcnt(8)
	s_waitcnt lgkmcnt(0)
	s_setprio 1
	s_barrier
	v_mfma_f32_16x16x32_bf16 v[60:63], v[128:131], v[172:175], v[60:63]
	v_mfma_f32_16x16x32_bf16 v[56:59], v[136:139], v[172:175], v[56:59]
	v_mfma_f32_16x16x32_bf16 v[52:55], v[128:131], v[184:187], v[52:55]
	v_mfma_f32_16x16x32_bf16 v[48:51], v[136:139], v[184:187], v[48:51]
	v_mfma_f32_16x16x32_bf16 v[44:47], v[128:131], v[192:195], v[44:47]
	v_mfma_f32_16x16x32_bf16 v[40:43], v[136:139], v[192:195], v[40:43]
	v_mfma_f32_16x16x32_bf16 v[36:39], v[128:131], v[202:205], v[36:39]
	v_mfma_f32_16x16x32_bf16 v[32:35], v[136:139], v[202:205], v[32:35]
	v_mfma_f32_16x16x32_bf16 v[60:63], v[132:135], v[176:179], v[60:63]
	v_mfma_f32_16x16x32_bf16 v[56:59], v[152:155], v[176:179], v[56:59]
	v_mfma_f32_16x16x32_bf16 v[52:55], v[132:135], v[188:191], v[52:55]
	v_mfma_f32_16x16x32_bf16 v[48:51], v[152:155], v[188:191], v[48:51]
	v_mfma_f32_16x16x32_bf16 v[44:47], v[132:135], v[196:199], v[44:47]
	v_mfma_f32_16x16x32_bf16 v[40:43], v[152:155], v[196:199], v[40:43]
	v_mfma_f32_16x16x32_bf16 v[36:39], v[132:135], v[206:209], v[36:39]
	v_mfma_f32_16x16x32_bf16 v[32:35], v[152:155], v[206:209], v[32:35]
	s_setprio 0
	s_setprio 1
	v_mfma_f32_16x16x32_bf16 v[28:31], v[156:159], v[172:175], v[28:31]
	v_mfma_f32_16x16x32_bf16 v[24:27], v[164:167], v[172:175], v[24:27]
	v_mfma_f32_16x16x32_bf16 v[20:23], v[156:159], v[184:187], v[20:23]
	v_mfma_f32_16x16x32_bf16 v[16:19], v[164:167], v[184:187], v[16:19]
	v_mfma_f32_16x16x32_bf16 v[12:15], v[156:159], v[192:195], v[12:15]
	v_mfma_f32_16x16x32_bf16 v[8:11], v[164:167], v[192:195], v[8:11]
	v_mfma_f32_16x16x32_bf16 v[4:7], v[156:159], v[202:205], v[4:7]
	v_mfma_f32_16x16x32_bf16 v[0:3], v[164:167], v[202:205], v[0:3]
	v_mfma_f32_16x16x32_bf16 v[28:31], v[160:163], v[176:179], v[28:31]
	v_mfma_f32_16x16x32_bf16 v[24:27], v[168:171], v[176:179], v[24:27]
	v_mfma_f32_16x16x32_bf16 v[20:23], v[160:163], v[188:191], v[20:23]
	v_mfma_f32_16x16x32_bf16 v[16:19], v[168:171], v[188:191], v[16:19]
	v_mfma_f32_16x16x32_bf16 v[12:15], v[160:163], v[196:199], v[12:15]
	v_mfma_f32_16x16x32_bf16 v[8:11], v[168:171], v[196:199], v[8:11]
	v_mfma_f32_16x16x32_bf16 v[4:7], v[160:163], v[206:209], v[4:7]
	v_mfma_f32_16x16x32_bf16 v[0:3], v[168:171], v[206:209], v[0:3]
	s_barrier
	s_setprio 0
	ds_read_b128 v[128:131], v248
	ds_read_b128 v[132:135], v248 offset:1024
	ds_read_b128 v[136:139], v248 offset:2048
	ds_read_b128 v[152:155], v248 offset:3072
	ds_read_b128 v[156:159], v249
	ds_read_b128 v[160:163], v249 offset:1024
	ds_read_b128 v[164:167], v249 offset:2048
	ds_read_b128 v[168:171], v249 offset:3072
	ds_read_b128 v[172:175], v182 offset:32768
	ds_read_b128 v[176:179], v182 offset:33792
	ds_read_b128 v[184:187], v182 offset:34816
	ds_read_b128 v[188:191], v182 offset:35840
	ds_read_b128 v[192:195], v182 offset:36864
	ds_read_b128 v[196:199], v182 offset:37888
	ds_read_b128 v[202:205], v182 offset:38912
	ds_read_b128 v[206:209], v182 offset:39936
	s_add_i32 s89, 0, 0x18000
	s_add_i32 s90, 0, 0x1c000
	s_add_u32 s68, s68, s56
	s_addc_u32 s69, s69, 0
	s_mov_b32 m0, s78
	v_lshl_add_u64 v[224:225], s[68:69], 0, v[140:141]
	global_load_lds_dwordx4 v[224:225], off
	v_lshl_add_u64 v[224:225], s[68:69], 0, v[144:145]
	s_mov_b32 m0, s79
	s_nop 0
	global_load_lds_dwordx4 v[224:225], off
	s_waitcnt vmcnt(8)
	s_waitcnt lgkmcnt(0)
	s_setprio 1
	s_barrier
	v_mfma_f32_16x16x32_bf16 v[124:127], v[128:131], v[172:175], v[124:127]
	v_mfma_f32_16x16x32_bf16 v[120:123], v[136:139], v[172:175], v[120:123]
	v_mfma_f32_16x16x32_bf16 v[116:119], v[128:131], v[184:187], v[116:119]
	v_mfma_f32_16x16x32_bf16 v[112:115], v[136:139], v[184:187], v[112:115]
	v_mfma_f32_16x16x32_bf16 v[108:111], v[128:131], v[192:195], v[108:111]
	v_mfma_f32_16x16x32_bf16 v[104:107], v[136:139], v[192:195], v[104:107]
	v_mfma_f32_16x16x32_bf16 v[100:103], v[128:131], v[202:205], v[100:103]
	v_mfma_f32_16x16x32_bf16 v[96:99], v[136:139], v[202:205], v[96:99]
	v_mfma_f32_16x16x32_bf16 v[124:127], v[132:135], v[176:179], v[124:127]
	v_mfma_f32_16x16x32_bf16 v[120:123], v[152:155], v[176:179], v[120:123]
	v_mfma_f32_16x16x32_bf16 v[116:119], v[132:135], v[188:191], v[116:119]
	v_mfma_f32_16x16x32_bf16 v[112:115], v[152:155], v[188:191], v[112:115]
	v_mfma_f32_16x16x32_bf16 v[108:111], v[132:135], v[196:199], v[108:111]
	v_mfma_f32_16x16x32_bf16 v[104:107], v[152:155], v[196:199], v[104:107]
	v_mfma_f32_16x16x32_bf16 v[100:103], v[132:135], v[206:209], v[100:103]
	v_mfma_f32_16x16x32_bf16 v[96:99], v[152:155], v[206:209], v[96:99]
	s_setprio 0
	s_setprio 1
	v_mfma_f32_16x16x32_bf16 v[92:95], v[156:159], v[172:175], v[92:95]
	v_mfma_f32_16x16x32_bf16 v[88:91], v[164:167], v[172:175], v[88:91]
	v_mfma_f32_16x16x32_bf16 v[84:87], v[156:159], v[184:187], v[84:87]
	v_mfma_f32_16x16x32_bf16 v[80:83], v[164:167], v[184:187], v[80:83]
	v_mfma_f32_16x16x32_bf16 v[76:79], v[156:159], v[192:195], v[76:79]
	v_mfma_f32_16x16x32_bf16 v[72:75], v[164:167], v[192:195], v[72:75]
	v_mfma_f32_16x16x32_bf16 v[68:71], v[156:159], v[202:205], v[68:71]
	v_mfma_f32_16x16x32_bf16 v[64:67], v[164:167], v[202:205], v[64:67]
	v_mfma_f32_16x16x32_bf16 v[92:95], v[160:163], v[176:179], v[92:95]
	v_mfma_f32_16x16x32_bf16 v[88:91], v[168:171], v[176:179], v[88:91]
	v_mfma_f32_16x16x32_bf16 v[84:87], v[160:163], v[188:191], v[84:87]
	v_mfma_f32_16x16x32_bf16 v[80:83], v[168:171], v[188:191], v[80:83]
	v_mfma_f32_16x16x32_bf16 v[76:79], v[160:163], v[196:199], v[76:79]
	v_mfma_f32_16x16x32_bf16 v[72:75], v[168:171], v[196:199], v[72:75]
	v_mfma_f32_16x16x32_bf16 v[68:71], v[160:163], v[206:209], v[68:71]
	v_mfma_f32_16x16x32_bf16 v[64:67], v[168:171], v[206:209], v[64:67]
	s_barrier
	s_setprio 0
	ds_read_b128 v[172:175], v182 offset:49152
	ds_read_b128 v[176:179], v182 offset:50176
	ds_read_b128 v[184:187], v182 offset:51200
	ds_read_b128 v[188:191], v182 offset:52224
	ds_read_b128 v[192:195], v182 offset:53248
	ds_read_b128 v[196:199], v182 offset:54272
	ds_read_b128 v[202:205], v182 offset:55296
	ds_read_b128 v[206:209], v182 offset:56320
	s_add_i32 s68, s89, s72
	v_lshl_add_u64 v[212:213], v[212:213], 0, s[64:65]
	s_mov_b32 m0, s68
	s_nop 0
	global_load_lds_dwordx4 v[212:213], off
	v_lshl_add_u64 v[212:213], v[214:215], 0, s[64:65]
	s_add_i32 m0, s68, 0x2000
	s_add_i32 s68, s90, s72
	global_load_lds_dwordx4 v[212:213], off
	v_lshl_add_u64 v[212:213], v[216:217], 0, s[64:65]
	s_mov_b32 m0, s68
	s_nop 0
	global_load_lds_dwordx4 v[212:213], off
	v_lshl_add_u64 v[212:213], v[218:219], 0, s[64:65]
	s_add_i32 m0, s68, 0x2000
	s_nop 0
	global_load_lds_dwordx4 v[212:213], off
	v_lshl_add_u64 v[212:213], v[220:221], 0, s[64:65]
	s_mov_b32 m0, s82
	s_nop 0
	global_load_lds_dwordx4 v[212:213], off
	v_lshl_add_u64 v[212:213], v[222:223], 0, s[64:65]
	s_mov_b32 m0, s83
	s_nop 0
	global_load_lds_dwordx4 v[212:213], off
	s_waitcnt vmcnt(8)
	s_waitcnt lgkmcnt(0)
	s_setprio 1
	s_barrier
	v_mfma_f32_16x16x32_bf16 v[60:63], v[128:131], v[172:175], v[60:63]
	v_mfma_f32_16x16x32_bf16 v[56:59], v[136:139], v[172:175], v[56:59]
	v_mfma_f32_16x16x32_bf16 v[52:55], v[128:131], v[184:187], v[52:55]
	v_mfma_f32_16x16x32_bf16 v[48:51], v[136:139], v[184:187], v[48:51]
	v_mfma_f32_16x16x32_bf16 v[44:47], v[128:131], v[192:195], v[44:47]
	v_mfma_f32_16x16x32_bf16 v[40:43], v[136:139], v[192:195], v[40:43]
	v_mfma_f32_16x16x32_bf16 v[36:39], v[128:131], v[202:205], v[36:39]
	v_mfma_f32_16x16x32_bf16 v[32:35], v[136:139], v[202:205], v[32:35]
	v_mfma_f32_16x16x32_bf16 v[60:63], v[132:135], v[176:179], v[60:63]
	v_mfma_f32_16x16x32_bf16 v[56:59], v[152:155], v[176:179], v[56:59]
	v_mfma_f32_16x16x32_bf16 v[52:55], v[132:135], v[188:191], v[52:55]
	v_mfma_f32_16x16x32_bf16 v[48:51], v[152:155], v[188:191], v[48:51]
	v_mfma_f32_16x16x32_bf16 v[44:47], v[132:135], v[196:199], v[44:47]
	v_mfma_f32_16x16x32_bf16 v[40:43], v[152:155], v[196:199], v[40:43]
	v_mfma_f32_16x16x32_bf16 v[36:39], v[132:135], v[206:209], v[36:39]
	v_mfma_f32_16x16x32_bf16 v[32:35], v[152:155], v[206:209], v[32:35]
	s_setprio 0
	s_setprio 1
	v_mfma_f32_16x16x32_bf16 v[28:31], v[156:159], v[172:175], v[28:31]
	v_mfma_f32_16x16x32_bf16 v[24:27], v[164:167], v[172:175], v[24:27]
	v_mfma_f32_16x16x32_bf16 v[20:23], v[156:159], v[184:187], v[20:23]
	v_mfma_f32_16x16x32_bf16 v[16:19], v[164:167], v[184:187], v[16:19]
	v_mfma_f32_16x16x32_bf16 v[12:15], v[156:159], v[192:195], v[12:15]
	v_mfma_f32_16x16x32_bf16 v[8:11], v[164:167], v[192:195], v[8:11]
	v_mfma_f32_16x16x32_bf16 v[4:7], v[156:159], v[202:205], v[4:7]
	v_mfma_f32_16x16x32_bf16 v[0:3], v[164:167], v[202:205], v[0:3]
	v_mfma_f32_16x16x32_bf16 v[28:31], v[160:163], v[176:179], v[28:31]
	v_mfma_f32_16x16x32_bf16 v[24:27], v[168:171], v[176:179], v[24:27]
	v_mfma_f32_16x16x32_bf16 v[20:23], v[160:163], v[188:191], v[20:23]
	v_mfma_f32_16x16x32_bf16 v[16:19], v[168:171], v[188:191], v[16:19]
	v_mfma_f32_16x16x32_bf16 v[12:15], v[160:163], v[196:199], v[12:15]
	v_mfma_f32_16x16x32_bf16 v[8:11], v[168:171], v[196:199], v[8:11]
	v_mfma_f32_16x16x32_bf16 v[4:7], v[160:163], v[206:209], v[4:7]
	v_mfma_f32_16x16x32_bf16 v[0:3], v[168:171], v[206:209], v[0:3]
	s_barrier
	s_setprio 0
	s_add_u32 s4, s4, 0x100
	s_addc_u32 s5, s5, 0
	s_add_u32 s70, s70, 0x100
	s_addc_u32 s71, s71, 0
	s_cmp_ge_u32 s88, s80
	s_mov_b32 s68, s88
	s_cbranch_scc0 .LBB0_974
	s_and_b64 vcc, exec, s[18:19]
	s_cbranch_vccz .LBB0_977
	s_barrier

.LBB0_1101:
	s_ashr_i32 s25, s24, 31
	s_lshl_b64 s[26:27], s[24:25], 20
	s_add_u32 s26, s48, s26
	s_addc_u32 s27, s49, s27
	s_and_b64 s[28:29], s[2:3], exec
	s_cselect_b32 s25, s27, s5
	s_cselect_b32 s61, s26, s4
	s_ashr_i32 s23, s22, 31
	s_lshl_b64 s[28:29], s[22:23], 20
	s_add_u32 s28, s50, s28
	s_addc_u32 s29, s51, s29
	s_and_b64 s[36:37], s[2:3], exec
	s_cselect_b32 s23, s29, s35
	s_cselect_b32 s62, s28, s34
	s_add_u32 s4, s4, 0x80080
	s_addc_u32 s5, s5, 0
	s_add_u32 s63, s34, 0x100
	s_addc_u32 s66, s35, 0
	s_mov_b32 s67, -2
	v_mov_b32_e32 v0, v172
	v_mov_b32_e32 v1, v172
	v_mov_b32_e32 v2, v172
	v_mov_b32_e32 v3, v172
	v_mov_b32_e32 v8, v172
	v_mov_b32_e32 v9, v172
	v_mov_b32_e32 v10, v172
	v_mov_b32_e32 v11, v172
	v_mov_b32_e32 v16, v172
	v_mov_b32_e32 v17, v172
	v_mov_b32_e32 v18, v172
	v_mov_b32_e32 v19, v172
	v_mov_b32_e32 v24, v172
	v_mov_b32_e32 v25, v172
	v_mov_b32_e32 v26, v172
	v_mov_b32_e32 v27, v172
	v_mov_b32_e32 v32, v172
	v_mov_b32_e32 v33, v172
	v_mov_b32_e32 v34, v172
	v_mov_b32_e32 v35, v172
	v_mov_b32_e32 v40, v172
	v_mov_b32_e32 v41, v172
	v_mov_b32_e32 v42, v172
	v_mov_b32_e32 v43, v172
	v_mov_b32_e32 v48, v172
	v_mov_b32_e32 v49, v172
	v_mov_b32_e32 v50, v172
	v_mov_b32_e32 v51, v172
	v_mov_b32_e32 v56, v172
	v_mov_b32_e32 v57, v172
	v_mov_b32_e32 v58, v172
	v_mov_b32_e32 v59, v172
	v_mov_b32_e32 v4, v172
	v_mov_b32_e32 v5, v172
	v_mov_b32_e32 v6, v172
	v_mov_b32_e32 v7, v172
	v_mov_b32_e32 v12, v172
	v_mov_b32_e32 v13, v172
	v_mov_b32_e32 v14, v172
	v_mov_b32_e32 v15, v172
	v_mov_b32_e32 v20, v172
	v_mov_b32_e32 v21, v172
	v_mov_b32_e32 v22, v172
	v_mov_b32_e32 v23, v172
	v_mov_b32_e32 v28, v172
	v_mov_b32_e32 v29, v172
	v_mov_b32_e32 v30, v172
	v_mov_b32_e32 v31, v172
	v_mov_b32_e32 v36, v172
	v_mov_b32_e32 v37, v172
	v_mov_b32_e32 v38, v172
	v_mov_b32_e32 v39, v172
	v_mov_b32_e32 v44, v172
	v_mov_b32_e32 v45, v172
	v_mov_b32_e32 v46, v172
	v_mov_b32_e32 v47, v172
	v_mov_b32_e32 v52, v172
	v_mov_b32_e32 v53, v172
	v_mov_b32_e32 v54, v172
	v_mov_b32_e32 v55, v172
	v_mov_b32_e32 v60, v172
	v_mov_b32_e32 v61, v172
	v_mov_b32_e32 v62, v172
	v_mov_b32_e32 v63, v172
	v_mov_b32_e32 v64, v172
	v_mov_b32_e32 v65, v172
	v_mov_b32_e32 v66, v172
	v_mov_b32_e32 v67, v172
	v_mov_b32_e32 v88, v172
	v_mov_b32_e32 v89, v172
	v_mov_b32_e32 v90, v172
	v_mov_b32_e32 v91, v172
	v_mov_b32_e32 v112, v172
	v_mov_b32_e32 v113, v172
	v_mov_b32_e32 v114, v172
	v_mov_b32_e32 v115, v172
	v_mov_b32_e32 v120, v172
	v_mov_b32_e32 v121, v172
	v_mov_b32_e32 v122, v172
	v_mov_b32_e32 v123, v172
	v_mov_b32_e32 v128, v172
	v_mov_b32_e32 v129, v172
	v_mov_b32_e32 v130, v172
	v_mov_b32_e32 v131, v172
	v_mov_b32_e32 v136, v172
	v_mov_b32_e32 v137, v172
	v_mov_b32_e32 v138, v172
	v_mov_b32_e32 v139, v172
	v_mov_b32_e32 v144, v172
	v_mov_b32_e32 v145, v172
	v_mov_b32_e32 v146, v172
	v_mov_b32_e32 v147, v172
	v_mov_b32_e32 v148, v172
	v_mov_b32_e32 v149, v172
	v_mov_b32_e32 v150, v172
	v_mov_b32_e32 v151, v172
	v_mov_b32_e32 v68, v172
	v_mov_b32_e32 v69, v172
	v_mov_b32_e32 v70, v172
	v_mov_b32_e32 v71, v172
	v_mov_b32_e32 v92, v172
	v_mov_b32_e32 v93, v172
	v_mov_b32_e32 v94, v172
	v_mov_b32_e32 v95, v172
	v_mov_b32_e32 v116, v172
	v_mov_b32_e32 v117, v172
	v_mov_b32_e32 v118, v172
	v_mov_b32_e32 v119, v172
	v_mov_b32_e32 v124, v172
	v_mov_b32_e32 v125, v172
	v_mov_b32_e32 v126, v172
	v_mov_b32_e32 v127, v172
	v_mov_b32_e32 v132, v172
	v_mov_b32_e32 v133, v172
	v_mov_b32_e32 v134, v172
	v_mov_b32_e32 v135, v172
	v_mov_b32_e32 v140, v172
	v_mov_b32_e32 v141, v172
	v_mov_b32_e32 v142, v172
	v_mov_b32_e32 v143, v172
	v_mov_b32_e32 v152, v172
	v_mov_b32_e32 v153, v172
	v_mov_b32_e32 v154, v172
	v_mov_b32_e32 v155, v172
	v_mov_b32_e32 v156, v172
	v_mov_b32_e32 v157, v172
	v_mov_b32_e32 v158, v172
	v_mov_b32_e32 v159, v172
	v_add_u32_e32 v246, 0x10000, v173
	v_add_u32_e32 v247, 0x14000, v173
	v_add_u32_e32 v248, 0x18000, v173
	v_add_u32_e32 v249, 0x1c000, v173
.LBB0_1102:
	ds_read_b128 v[72:75], v246
	ds_read_b128 v[76:79], v246 offset:1024
	ds_read_b128 v[80:83], v246 offset:2048
	ds_read_b128 v[84:87], v246 offset:3072
	ds_read_b128 v[96:99], v247
	ds_read_b128 v[100:103], v247 offset:1024
	ds_read_b128 v[104:107], v247 offset:2048
	ds_read_b128 v[108:111], v247 offset:3072
	ds_read_b128 v[176:179], v174
	ds_read_b128 v[180:183], v174 offset:1024
	ds_read_b128 v[184:187], v174 offset:2048
	ds_read_b128 v[188:191], v174 offset:3072
	ds_read_b128 v[192:195], v174 offset:4096
	ds_read_b128 v[196:199], v174 offset:5120
	ds_read_b128 v[202:205], v174 offset:6144
	ds_read_b128 v[206:209], v174 offset:7168
	s_add_u32 s34, s4, 0xfff80080
	s_addc_u32 s35, s5, -1
	s_add_i32 s68, 0, 0x10000
	s_cmp_eq_u32 s67, 28
	s_cselect_b32 s37, s25, s35
	s_cselect_b32 s36, s61, s34
	s_cselect_b32 s35, s23, s66
	s_cselect_b32 s34, s62, s63
	s_add_i32 s70, 0, 0x14000
	v_lshl_add_u64 v[170:171], s[4:5], 0, v[166:167]
	s_add_i32 m0, s31, 0xc000
	s_nop 0
	global_load_lds_dwordx4 v[170:171], off
	v_lshl_add_u64 v[170:171], s[4:5], 0, v[168:169]
	s_add_i32 m0, s31, 0xe000
	s_nop 0
	global_load_lds_dwordx4 v[170:171], off
	s_add_u32 vcc_lo, s4, 0xfff80000
	s_addc_u32 vcc_hi, s5, -1
	s_mov_b32 m0, s55
	s_nop 0
	global_load_lds_dwordx4 v164, vcc
	s_mov_b32 m0, s56
	s_nop 0
	global_load_lds_dwordx4 v162, vcc
	s_waitcnt vmcnt(4)
	s_waitcnt lgkmcnt(0)
	s_setprio 1
	s_barrier
	v_mfma_f32_16x16x32_bf16 v[156:159], v[72:75], v[176:179], v[156:159]
	v_mfma_f32_16x16x32_bf16 v[152:155], v[80:83], v[176:179], v[152:155]
	v_mfma_f32_16x16x32_bf16 v[140:143], v[72:75], v[184:187], v[140:143]
	v_mfma_f32_16x16x32_bf16 v[132:135], v[80:83], v[184:187], v[132:135]
	v_mfma_f32_16x16x32_bf16 v[124:127], v[72:75], v[192:195], v[124:127]
	v_mfma_f32_16x16x32_bf16 v[116:119], v[80:83], v[192:195], v[116:119]
	v_mfma_f32_16x16x32_bf16 v[92:95], v[72:75], v[202:205], v[92:95]
	v_mfma_f32_16x16x32_bf16 v[68:71], v[80:83], v[202:205], v[68:71]
	v_mfma_f32_16x16x32_bf16 v[156:159], v[76:79], v[180:183], v[156:159]
	v_mfma_f32_16x16x32_bf16 v[152:155], v[84:87], v[180:183], v[152:155]
	v_mfma_f32_16x16x32_bf16 v[140:143], v[76:79], v[188:191], v[140:143]
	v_mfma_f32_16x16x32_bf16 v[132:135], v[84:87], v[188:191], v[132:135]
	v_mfma_f32_16x16x32_bf16 v[124:127], v[76:79], v[196:199], v[124:127]
	v_mfma_f32_16x16x32_bf16 v[116:119], v[84:87], v[196:199], v[116:119]
	v_mfma_f32_16x16x32_bf16 v[92:95], v[76:79], v[206:209], v[92:95]
	v_mfma_f32_16x16x32_bf16 v[68:71], v[84:87], v[206:209], v[68:71]
	s_setprio 0
	s_setprio 1
	v_mfma_f32_16x16x32_bf16 v[148:151], v[96:99], v[176:179], v[148:151]
	v_mfma_f32_16x16x32_bf16 v[144:147], v[104:107], v[176:179], v[144:147]
	v_mfma_f32_16x16x32_bf16 v[136:139], v[96:99], v[184:187], v[136:139]
	v_mfma_f32_16x16x32_bf16 v[128:131], v[104:107], v[184:187], v[128:131]
	v_mfma_f32_16x16x32_bf16 v[120:123], v[96:99], v[192:195], v[120:123]
	v_mfma_f32_16x16x32_bf16 v[112:115], v[104:107], v[192:195], v[112:115]
	v_mfma_f32_16x16x32_bf16 v[88:91], v[96:99], v[202:205], v[88:91]
	v_mfma_f32_16x16x32_bf16 v[64:67], v[104:107], v[202:205], v[64:67]
	v_mfma_f32_16x16x32_bf16 v[148:151], v[100:103], v[180:183], v[148:151]
	v_mfma_f32_16x16x32_bf16 v[144:147], v[108:111], v[180:183], v[144:147]
	v_mfma_f32_16x16x32_bf16 v[136:139], v[100:103], v[188:191], v[136:139]
	v_mfma_f32_16x16x32_bf16 v[128:131], v[108:111], v[188:191], v[128:131]
	v_mfma_f32_16x16x32_bf16 v[120:123], v[100:103], v[196:199], v[120:123]
	v_mfma_f32_16x16x32_bf16 v[112:115], v[108:111], v[196:199], v[112:115]
	v_mfma_f32_16x16x32_bf16 v[88:91], v[100:103], v[206:209], v[88:91]
	v_mfma_f32_16x16x32_bf16 v[64:67], v[108:111], v[206:209], v[64:67]
	s_barrier
	s_setprio 0
	ds_read_b128 v[176:179], v174 offset:16384
	ds_read_b128 v[180:183], v174 offset:17408
	ds_read_b128 v[184:187], v174 offset:18432
	ds_read_b128 v[188:191], v174 offset:19456
	ds_read_b128 v[192:195], v174 offset:20480
	ds_read_b128 v[196:199], v174 offset:21504
	ds_read_b128 v[202:205], v174 offset:22528
	ds_read_b128 v[206:209], v174 offset:23552
	s_add_i32 s68, s68, s53
	v_lshl_add_u64 v[170:171], s[34:35], 0, v[200:201]
	s_mov_b32 m0, s68
	s_nop 0
	global_load_lds_dwordx4 v[170:171], off
	s_add_i32 m0, s68, 0x2000
	s_add_u32 s68, s34, 0x80000
	v_lshl_add_u64 v[212:213], s[34:35], 0, v[160:161]
	s_addc_u32 s69, s35, 0
	s_add_i32 s70, s70, s53
	global_load_lds_dwordx4 v[212:213], off
	v_lshl_add_u64 v[214:215], s[68:69], 0, v[200:201]
	s_mov_b32 m0, s70
	s_nop 0
	global_load_lds_dwordx4 v[214:215], off
	v_lshl_add_u64 v[214:215], s[68:69], 0, v[160:161]
	s_add_i32 m0, s70, 0x2000
	s_nop 0
	global_load_lds_dwordx4 v[214:215], off
	s_waitcnt vmcnt(4)
	s_waitcnt lgkmcnt(0)
	s_setprio 1
	s_barrier
	v_mfma_f32_16x16x32_bf16 v[60:63], v[72:75], v[176:179], v[60:63]
	v_mfma_f32_16x16x32_bf16 v[52:55], v[80:83], v[176:179], v[52:55]
	v_mfma_f32_16x16x32_bf16 v[44:47], v[72:75], v[184:187], v[44:47]
	v_mfma_f32_16x16x32_bf16 v[36:39], v[80:83], v[184:187], v[36:39]
	v_mfma_f32_16x16x32_bf16 v[28:31], v[72:75], v[192:195], v[28:31]
	v_mfma_f32_16x16x32_bf16 v[20:23], v[80:83], v[192:195], v[20:23]
	v_mfma_f32_16x16x32_bf16 v[12:15], v[72:75], v[202:205], v[12:15]
	v_mfma_f32_16x16x32_bf16 v[4:7], v[80:83], v[202:205], v[4:7]
	v_mfma_f32_16x16x32_bf16 v[60:63], v[76:79], v[180:183], v[60:63]
	v_mfma_f32_16x16x32_bf16 v[52:55], v[84:87], v[180:183], v[52:55]
	v_mfma_f32_16x16x32_bf16 v[44:47], v[76:79], v[188:191], v[44:47]
	v_mfma_f32_16x16x32_bf16 v[36:39], v[84:87], v[188:191], v[36:39]
	v_mfma_f32_16x16x32_bf16 v[28:31], v[76:79], v[196:199], v[28:31]
	v_mfma_f32_16x16x32_bf16 v[20:23], v[84:87], v[196:199], v[20:23]
	v_mfma_f32_16x16x32_bf16 v[12:15], v[76:79], v[206:209], v[12:15]
	v_mfma_f32_16x16x32_bf16 v[4:7], v[84:87], v[206:209], v[4:7]
	s_setprio 0
	s_setprio 1
	v_mfma_f32_16x16x32_bf16 v[56:59], v[96:99], v[176:179], v[56:59]
	v_mfma_f32_16x16x32_bf16 v[48:51], v[104:107], v[176:179], v[48:51]
	v_mfma_f32_16x16x32_bf16 v[40:43], v[96:99], v[184:187], v[40:43]
	v_mfma_f32_16x16x32_bf16 v[32:35], v[104:107], v[184:187], v[32:35]
	v_mfma_f32_16x16x32_bf16 v[24:27], v[96:99], v[192:195], v[24:27]
	v_mfma_f32_16x16x32_bf16 v[16:19], v[104:107], v[192:195], v[16:19]
	v_mfma_f32_16x16x32_bf16 v[8:11], v[96:99], v[202:205], v[8:11]
	v_mfma_f32_16x16x32_bf16 v[0:3], v[104:107], v[202:205], v[0:3]
	v_mfma_f32_16x16x32_bf16 v[56:59], v[100:103], v[180:183], v[56:59]
	v_mfma_f32_16x16x32_bf16 v[48:51], v[108:111], v[180:183], v[48:51]
	v_mfma_f32_16x16x32_bf16 v[40:43], v[100:103], v[188:191], v[40:43]
	v_mfma_f32_16x16x32_bf16 v[32:35], v[108:111], v[188:191], v[32:35]
	v_mfma_f32_16x16x32_bf16 v[24:27], v[100:103], v[196:199], v[24:27]
	v_mfma_f32_16x16x32_bf16 v[16:19], v[108:111], v[196:199], v[16:19]
	v_mfma_f32_16x16x32_bf16 v[8:11], v[100:103], v[206:209], v[8:11]
	v_mfma_f32_16x16x32_bf16 v[0:3], v[108:111], v[206:209], v[0:3]
	s_barrier
	s_setprio 0
	ds_read_b128 v[72:75], v248
	ds_read_b128 v[76:79], v248 offset:1024
	ds_read_b128 v[80:83], v248 offset:2048
	ds_read_b128 v[84:87], v248 offset:3072
	ds_read_b128 v[96:99], v249
	ds_read_b128 v[100:103], v249 offset:1024
	ds_read_b128 v[104:107], v249 offset:2048
	ds_read_b128 v[108:111], v249 offset:3072
	ds_read_b128 v[176:179], v174 offset:32768
	ds_read_b128 v[180:183], v174 offset:33792
	ds_read_b128 v[184:187], v174 offset:34816
	ds_read_b128 v[188:191], v174 offset:35840
	ds_read_b128 v[192:195], v174 offset:36864
	ds_read_b128 v[196:199], v174 offset:37888
	ds_read_b128 v[202:205], v174 offset:38912
	ds_read_b128 v[206:209], v174 offset:39936
	s_add_i32 s68, 0, 0x18000
	s_add_i32 s69, 0, 0x1c000
	s_mov_b32 m0, s31
	s_nop 0
	global_load_lds_dwordx4 v164, s[36:37]
	s_mov_b32 m0, s42
	s_nop 0
	global_load_lds_dwordx4 v162, s[36:37]
	s_add_u32 s36, s36, 0x80000
	s_addc_u32 s37, s37, 0
	s_mov_b32 m0, s43
	v_lshl_add_u64 v[218:219], s[36:37], 0, v[164:165]
	global_load_lds_dwordx4 v[218:219], off
	v_lshl_add_u64 v[218:219], s[36:37], 0, v[162:163]
	s_mov_b32 m0, s54
	s_nop 0
	global_load_lds_dwordx4 v[218:219], off
	s_waitcnt vmcnt(4)
	s_waitcnt lgkmcnt(0)
	s_setprio 1
	s_barrier
	v_mfma_f32_16x16x32_bf16 v[156:159], v[72:75], v[176:179], v[156:159]
	v_mfma_f32_16x16x32_bf16 v[152:155], v[80:83], v[176:179], v[152:155]
	v_mfma_f32_16x16x32_bf16 v[140:143], v[72:75], v[184:187], v[140:143]
	v_mfma_f32_16x16x32_bf16 v[132:135], v[80:83], v[184:187], v[132:135]
	v_mfma_f32_16x16x32_bf16 v[124:127], v[72:75], v[192:195], v[124:127]
	v_mfma_f32_16x16x32_bf16 v[116:119], v[80:83], v[192:195], v[116:119]
	v_mfma_f32_16x16x32_bf16 v[92:95], v[72:75], v[202:205], v[92:95]
	v_mfma_f32_16x16x32_bf16 v[68:71], v[80:83], v[202:205], v[68:71]
	v_mfma_f32_16x16x32_bf16 v[156:159], v[76:79], v[180:183], v[156:159]
	v_mfma_f32_16x16x32_bf16 v[152:155], v[84:87], v[180:183], v[152:155]
	v_mfma_f32_16x16x32_bf16 v[140:143], v[76:79], v[188:191], v[140:143]
	v_mfma_f32_16x16x32_bf16 v[132:135], v[84:87], v[188:191], v[132:135]
	v_mfma_f32_16x16x32_bf16 v[124:127], v[76:79], v[196:199], v[124:127]
	v_mfma_f32_16x16x32_bf16 v[116:119], v[84:87], v[196:199], v[116:119]
	v_mfma_f32_16x16x32_bf16 v[92:95], v[76:79], v[206:209], v[92:95]
	v_mfma_f32_16x16x32_bf16 v[68:71], v[84:87], v[206:209], v[68:71]
	s_setprio 0
	s_setprio 1
	v_mfma_f32_16x16x32_bf16 v[148:151], v[96:99], v[176:179], v[148:151]
	v_mfma_f32_16x16x32_bf16 v[144:147], v[104:107], v[176:179], v[144:147]
	v_mfma_f32_16x16x32_bf16 v[136:139], v[96:99], v[184:187], v[136:139]
	v_mfma_f32_16x16x32_bf16 v[128:131], v[104:107], v[184:187], v[128:131]
	v_mfma_f32_16x16x32_bf16 v[120:123], v[96:99], v[192:195], v[120:123]
	v_mfma_f32_16x16x32_bf16 v[112:115], v[104:107], v[192:195], v[112:115]
	v_mfma_f32_16x16x32_bf16 v[88:91], v[96:99], v[202:205], v[88:91]
	v_mfma_f32_16x16x32_bf16 v[64:67], v[104:107], v[202:205], v[64:67]
	v_mfma_f32_16x16x32_bf16 v[148:151], v[100:103], v[180:183], v[148:151]
	v_mfma_f32_16x16x32_bf16 v[144:147], v[108:111], v[180:183], v[144:147]
	v_mfma_f32_16x16x32_bf16 v[136:139], v[100:103], v[188:191], v[136:139]
	v_mfma_f32_16x16x32_bf16 v[128:131], v[108:111], v[188:191], v[128:131]
	v_mfma_f32_16x16x32_bf16 v[120:123], v[100:103], v[196:199], v[120:123]
	v_mfma_f32_16x16x32_bf16 v[112:115], v[108:111], v[196:199], v[112:115]
	v_mfma_f32_16x16x32_bf16 v[88:91], v[100:103], v[206:209], v[88:91]
	v_mfma_f32_16x16x32_bf16 v[64:67], v[108:111], v[206:209], v[64:67]
	s_barrier
	s_setprio 0
	ds_read_b128 v[176:179], v174 offset:49152
	ds_read_b128 v[180:183], v174 offset:50176
	ds_read_b128 v[184:187], v174 offset:51200
	ds_read_b128 v[188:191], v174 offset:52224
	ds_read_b128 v[192:195], v174 offset:53248
	ds_read_b128 v[196:199], v174 offset:54272
	ds_read_b128 v[202:205], v174 offset:55296
	ds_read_b128 v[206:209], v174 offset:56320
	s_add_i32 s36, s68, s53
	v_lshl_add_u64 v[170:171], v[170:171], 0, s[64:65]
	s_mov_b32 m0, s36
	s_nop 0
	global_load_lds_dwordx4 v[170:171], off
	s_add_i32 m0, s36, 0x2000
	s_add_u32 s34, s34, 0x80080
	v_lshl_add_u64 v[170:171], v[212:213], 0, s[64:65]
	s_addc_u32 s35, s35, 0
	s_add_i32 s36, s69, s53
	global_load_lds_dwordx4 v[170:171], off
	v_lshl_add_u64 v[170:171], s[34:35], 0, v[200:201]
	s_mov_b32 m0, s36
	s_nop 0
	global_load_lds_dwordx4 v[170:171], off
	v_lshl_add_u64 v[170:171], s[34:35], 0, v[160:161]
	s_add_i32 m0, s36, 0x2000
	s_nop 0
	global_load_lds_dwordx4 v[170:171], off
	s_waitcnt vmcnt(4)
	s_waitcnt lgkmcnt(0)
	s_setprio 1
	s_barrier
	v_mfma_f32_16x16x32_bf16 v[60:63], v[72:75], v[176:179], v[60:63]
	v_mfma_f32_16x16x32_bf16 v[52:55], v[80:83], v[176:179], v[52:55]
	v_mfma_f32_16x16x32_bf16 v[44:47], v[72:75], v[184:187], v[44:47]
	v_mfma_f32_16x16x32_bf16 v[36:39], v[80:83], v[184:187], v[36:39]
	v_mfma_f32_16x16x32_bf16 v[28:31], v[72:75], v[192:195], v[28:31]
	v_mfma_f32_16x16x32_bf16 v[20:23], v[80:83], v[192:195], v[20:23]
	v_mfma_f32_16x16x32_bf16 v[12:15], v[72:75], v[202:205], v[12:15]
	v_mfma_f32_16x16x32_bf16 v[4:7], v[80:83], v[202:205], v[4:7]
	v_mfma_f32_16x16x32_bf16 v[60:63], v[76:79], v[180:183], v[60:63]
	v_mfma_f32_16x16x32_bf16 v[52:55], v[84:87], v[180:183], v[52:55]
	v_mfma_f32_16x16x32_bf16 v[44:47], v[76:79], v[188:191], v[44:47]
	v_mfma_f32_16x16x32_bf16 v[36:39], v[84:87], v[188:191], v[36:39]
	v_mfma_f32_16x16x32_bf16 v[28:31], v[76:79], v[196:199], v[28:31]
	v_mfma_f32_16x16x32_bf16 v[20:23], v[84:87], v[196:199], v[20:23]
	v_mfma_f32_16x16x32_bf16 v[12:15], v[76:79], v[206:209], v[12:15]
	v_mfma_f32_16x16x32_bf16 v[4:7], v[84:87], v[206:209], v[4:7]
	s_setprio 0
	s_setprio 1
	v_mfma_f32_16x16x32_bf16 v[56:59], v[96:99], v[176:179], v[56:59]
	v_mfma_f32_16x16x32_bf16 v[48:51], v[104:107], v[176:179], v[48:51]
	v_mfma_f32_16x16x32_bf16 v[40:43], v[96:99], v[184:187], v[40:43]
	v_mfma_f32_16x16x32_bf16 v[32:35], v[104:107], v[184:187], v[32:35]
	v_mfma_f32_16x16x32_bf16 v[24:27], v[96:99], v[192:195], v[24:27]
	v_mfma_f32_16x16x32_bf16 v[16:19], v[104:107], v[192:195], v[16:19]
	v_mfma_f32_16x16x32_bf16 v[8:11], v[96:99], v[202:205], v[8:11]
	v_mfma_f32_16x16x32_bf16 v[0:3], v[104:107], v[202:205], v[0:3]
	v_mfma_f32_16x16x32_bf16 v[56:59], v[100:103], v[180:183], v[56:59]
	v_mfma_f32_16x16x32_bf16 v[48:51], v[108:111], v[180:183], v[48:51]
	v_mfma_f32_16x16x32_bf16 v[40:43], v[100:103], v[188:191], v[40:43]
	v_mfma_f32_16x16x32_bf16 v[32:35], v[108:111], v[188:191], v[32:35]
	v_mfma_f32_16x16x32_bf16 v[24:27], v[100:103], v[196:199], v[24:27]
	v_mfma_f32_16x16x32_bf16 v[16:19], v[108:111], v[196:199], v[16:19]
	v_mfma_f32_16x16x32_bf16 v[8:11], v[100:103], v[206:209], v[8:11]
	v_mfma_f32_16x16x32_bf16 v[0:3], v[108:111], v[206:209], v[0:3]
	s_barrier
	s_setprio 0
	s_add_i32 s67, s67, 2
	s_add_u32 s4, s4, 0x100
	s_addc_u32 s5, s5, 0
	s_add_u32 s63, s63, 0x100
	s_addc_u32 s66, s66, 0
	s_cmp_gt_u32 s67, 29
	s_cbranch_scc0 .LBB0_1102
	s_and_b64 vcc, exec, s[20:21]
	s_cbranch_vccz .LBB0_1105
	s_barrier

.LBB0_1147:
	s_andn2_b64 vcc, exec, s[14:15]
	v_mov_b32_e32 v127, v138
	v_mov_b32_e32 v126, v138
	v_mov_b32_e32 v125, v138
	v_mov_b32_e32 v124, v138
	v_mov_b32_e32 v123, v138
	v_mov_b32_e32 v122, v138
	v_mov_b32_e32 v121, v138
	v_mov_b32_e32 v120, v138
	v_mov_b32_e32 v111, v138
	v_mov_b32_e32 v110, v138
	v_mov_b32_e32 v109, v138
	v_mov_b32_e32 v108, v138
	v_mov_b32_e32 v107, v138
	v_mov_b32_e32 v106, v138
	v_mov_b32_e32 v105, v138
	v_mov_b32_e32 v104, v138
	v_mov_b32_e32 v95, v138
	v_mov_b32_e32 v94, v138
	v_mov_b32_e32 v93, v138
	v_mov_b32_e32 v92, v138
	v_mov_b32_e32 v91, v138
	v_mov_b32_e32 v90, v138
	v_mov_b32_e32 v89, v138
	v_mov_b32_e32 v88, v138
	v_mov_b32_e32 v79, v138
	v_mov_b32_e32 v78, v138
	v_mov_b32_e32 v77, v138
	v_mov_b32_e32 v76, v138
	v_mov_b32_e32 v75, v138
	v_mov_b32_e32 v74, v138
	v_mov_b32_e32 v73, v138
	v_mov_b32_e32 v72, v138
	v_mov_b32_e32 v119, v138
	v_mov_b32_e32 v118, v138
	v_mov_b32_e32 v117, v138
	v_mov_b32_e32 v116, v138
	v_mov_b32_e32 v115, v138
	v_mov_b32_e32 v114, v138
	v_mov_b32_e32 v113, v138
	v_mov_b32_e32 v112, v138
	v_mov_b32_e32 v103, v138
	v_mov_b32_e32 v102, v138
	v_mov_b32_e32 v101, v138
	v_mov_b32_e32 v100, v138
	v_mov_b32_e32 v99, v138
	v_mov_b32_e32 v98, v138
	v_mov_b32_e32 v97, v138
	v_mov_b32_e32 v96, v138
	v_mov_b32_e32 v87, v138
	v_mov_b32_e32 v86, v138
	v_mov_b32_e32 v85, v138
	v_mov_b32_e32 v84, v138
	v_mov_b32_e32 v83, v138
	v_mov_b32_e32 v82, v138
	v_mov_b32_e32 v81, v138
	v_mov_b32_e32 v80, v138
	v_mov_b32_e32 v71, v138
	v_mov_b32_e32 v70, v138
	v_mov_b32_e32 v69, v138
	v_mov_b32_e32 v68, v138
	v_mov_b32_e32 v67, v138
	v_mov_b32_e32 v66, v138
	v_mov_b32_e32 v65, v138
	v_mov_b32_e32 v64, v138
	v_mov_b32_e32 v63, v138
	v_mov_b32_e32 v62, v138
	v_mov_b32_e32 v61, v138
	v_mov_b32_e32 v60, v138
	v_mov_b32_e32 v59, v138
	v_mov_b32_e32 v58, v138
	v_mov_b32_e32 v57, v138
	v_mov_b32_e32 v56, v138
	v_mov_b32_e32 v47, v138
	v_mov_b32_e32 v46, v138
	v_mov_b32_e32 v45, v138
	v_mov_b32_e32 v44, v138
	v_mov_b32_e32 v43, v138
	v_mov_b32_e32 v42, v138
	v_mov_b32_e32 v41, v138
	v_mov_b32_e32 v40, v138
	v_mov_b32_e32 v31, v138
	v_mov_b32_e32 v30, v138
	v_mov_b32_e32 v29, v138
	v_mov_b32_e32 v28, v138
	v_mov_b32_e32 v27, v138
	v_mov_b32_e32 v26, v138
	v_mov_b32_e32 v25, v138
	v_mov_b32_e32 v24, v138
	v_mov_b32_e32 v15, v138
	v_mov_b32_e32 v14, v138
	v_mov_b32_e32 v13, v138
	v_mov_b32_e32 v12, v138
	v_mov_b32_e32 v11, v138
	v_mov_b32_e32 v10, v138
	v_mov_b32_e32 v9, v138
	v_mov_b32_e32 v8, v138
	v_mov_b32_e32 v55, v138
	v_mov_b32_e32 v54, v138
	v_mov_b32_e32 v53, v138
	v_mov_b32_e32 v52, v138
	v_mov_b32_e32 v51, v138
	v_mov_b32_e32 v50, v138
	v_mov_b32_e32 v49, v138
	v_mov_b32_e32 v48, v138
	v_mov_b32_e32 v39, v138
	v_mov_b32_e32 v38, v138
	v_mov_b32_e32 v37, v138
	v_mov_b32_e32 v36, v138
	v_mov_b32_e32 v35, v138
	v_mov_b32_e32 v34, v138
	v_mov_b32_e32 v33, v138
	v_mov_b32_e32 v32, v138
	v_mov_b32_e32 v23, v138
	v_mov_b32_e32 v22, v138
	v_mov_b32_e32 v21, v138
	v_mov_b32_e32 v20, v138
	v_mov_b32_e32 v19, v138
	v_mov_b32_e32 v18, v138
	v_mov_b32_e32 v17, v138
	v_mov_b32_e32 v16, v138
	v_mov_b32_e32 v7, v138
	v_mov_b32_e32 v6, v138
	v_mov_b32_e32 v5, v138
	v_mov_b32_e32 v4, v138
	v_mov_b32_e32 v3, v138
	v_mov_b32_e32 v2, v138
	v_mov_b32_e32 v1, v138
	v_mov_b32_e32 v0, v138
	s_cbranch_vccnz .LBB0_1151
	s_add_u32 s20, s20, 0x80
	s_addc_u32 s21, s21, 0
	s_add_u32 s49, s22, 0x100
	s_addc_u32 s50, s23, 0
	s_mov_b32 s22, 0
	v_mov_b32_e32 v0, v138
	v_mov_b32_e32 v1, v138
	v_mov_b32_e32 v2, v138
	v_mov_b32_e32 v3, v138
	v_mov_b32_e32 v4, v138
	v_mov_b32_e32 v5, v138
	v_mov_b32_e32 v6, v138
	v_mov_b32_e32 v7, v138
	v_mov_b32_e32 v16, v138
	v_mov_b32_e32 v17, v138
	v_mov_b32_e32 v18, v138
	v_mov_b32_e32 v19, v138
	v_mov_b32_e32 v20, v138
	v_mov_b32_e32 v21, v138
	v_mov_b32_e32 v22, v138
	v_mov_b32_e32 v23, v138
	v_mov_b32_e32 v32, v138
	v_mov_b32_e32 v33, v138
	v_mov_b32_e32 v34, v138
	v_mov_b32_e32 v35, v138
	v_mov_b32_e32 v36, v138
	v_mov_b32_e32 v37, v138
	v_mov_b32_e32 v38, v138
	v_mov_b32_e32 v39, v138
	v_mov_b32_e32 v48, v138
	v_mov_b32_e32 v49, v138
	v_mov_b32_e32 v50, v138
	v_mov_b32_e32 v51, v138
	v_mov_b32_e32 v52, v138
	v_mov_b32_e32 v53, v138
	v_mov_b32_e32 v54, v138
	v_mov_b32_e32 v55, v138
	v_mov_b32_e32 v8, v138
	v_mov_b32_e32 v9, v138
	v_mov_b32_e32 v10, v138
	v_mov_b32_e32 v11, v138
	v_mov_b32_e32 v12, v138
	v_mov_b32_e32 v13, v138
	v_mov_b32_e32 v14, v138
	v_mov_b32_e32 v15, v138
	v_mov_b32_e32 v24, v138
	v_mov_b32_e32 v25, v138
	v_mov_b32_e32 v26, v138
	v_mov_b32_e32 v27, v138
	v_mov_b32_e32 v28, v138
	v_mov_b32_e32 v29, v138
	v_mov_b32_e32 v30, v138
	v_mov_b32_e32 v31, v138
	v_mov_b32_e32 v40, v138
	v_mov_b32_e32 v41, v138
	v_mov_b32_e32 v42, v138
	v_mov_b32_e32 v43, v138
	v_mov_b32_e32 v44, v138
	v_mov_b32_e32 v45, v138
	v_mov_b32_e32 v46, v138
	v_mov_b32_e32 v47, v138
	v_mov_b32_e32 v56, v138
	v_mov_b32_e32 v57, v138
	v_mov_b32_e32 v58, v138
	v_mov_b32_e32 v59, v138
	v_mov_b32_e32 v60, v138
	v_mov_b32_e32 v61, v138
	v_mov_b32_e32 v62, v138
	v_mov_b32_e32 v63, v138
	v_mov_b32_e32 v64, v138
	v_mov_b32_e32 v65, v138
	v_mov_b32_e32 v66, v138
	v_mov_b32_e32 v67, v138
	v_mov_b32_e32 v68, v138
	v_mov_b32_e32 v69, v138
	v_mov_b32_e32 v70, v138
	v_mov_b32_e32 v71, v138
	v_mov_b32_e32 v80, v138
	v_mov_b32_e32 v81, v138
	v_mov_b32_e32 v82, v138
	v_mov_b32_e32 v83, v138
	v_mov_b32_e32 v84, v138
	v_mov_b32_e32 v85, v138
	v_mov_b32_e32 v86, v138
	v_mov_b32_e32 v87, v138
	v_mov_b32_e32 v96, v138
	v_mov_b32_e32 v97, v138
	v_mov_b32_e32 v98, v138
	v_mov_b32_e32 v99, v138
	v_mov_b32_e32 v100, v138
	v_mov_b32_e32 v101, v138
	v_mov_b32_e32 v102, v138
	v_mov_b32_e32 v103, v138
	v_mov_b32_e32 v112, v138
	v_mov_b32_e32 v113, v138
	v_mov_b32_e32 v114, v138
	v_mov_b32_e32 v115, v138
	v_mov_b32_e32 v116, v138
	v_mov_b32_e32 v117, v138
	v_mov_b32_e32 v118, v138
	v_mov_b32_e32 v119, v138
	v_mov_b32_e32 v72, v138
	v_mov_b32_e32 v73, v138
	v_mov_b32_e32 v74, v138
	v_mov_b32_e32 v75, v138
	v_mov_b32_e32 v76, v138
	v_mov_b32_e32 v77, v138
	v_mov_b32_e32 v78, v138
	v_mov_b32_e32 v79, v138
	v_mov_b32_e32 v88, v138
	v_mov_b32_e32 v89, v138
	v_mov_b32_e32 v90, v138
	v_mov_b32_e32 v91, v138
	v_mov_b32_e32 v92, v138
	v_mov_b32_e32 v93, v138
	v_mov_b32_e32 v94, v138
	v_mov_b32_e32 v95, v138
	v_mov_b32_e32 v104, v138
	v_mov_b32_e32 v105, v138
	v_mov_b32_e32 v106, v138
	v_mov_b32_e32 v107, v138
	v_mov_b32_e32 v108, v138
	v_mov_b32_e32 v109, v138
	v_mov_b32_e32 v110, v138
	v_mov_b32_e32 v111, v138
	v_mov_b32_e32 v120, v138
	v_mov_b32_e32 v121, v138
	v_mov_b32_e32 v122, v138
	v_mov_b32_e32 v123, v138
	v_mov_b32_e32 v124, v138
	v_mov_b32_e32 v125, v138
	v_mov_b32_e32 v126, v138
	v_mov_b32_e32 v127, v138
	v_add_u32_e32 v246, 0x10000, v139
	v_add_u32_e32 v247, 0x14000, v139
	v_add_u32_e32 v248, 0x18000, v139
	v_add_u32_e32 v249, 0x1c000, v139
.LBB0_1149:
	ds_read_b128 v[142:145], v246
	ds_read_b128 v[146:149], v246 offset:1024
	ds_read_b128 v[150:153], v246 offset:2048
	ds_read_b128 v[154:157], v246 offset:3072
	ds_read_b128 v[158:161], v247
	ds_read_b128 v[162:165], v247 offset:1024
	ds_read_b128 v[166:169], v247 offset:2048
	ds_read_b128 v[170:173], v247 offset:3072
	ds_read_b128 v[174:177], v140
	ds_read_b128 v[178:181], v140 offset:1024
	ds_read_b128 v[182:185], v140 offset:2048
	ds_read_b128 v[186:189], v140 offset:3072
	ds_read_b128 v[190:193], v140 offset:4096
	ds_read_b128 v[194:197], v140 offset:5120
	ds_read_b128 v[202:205], v140 offset:6144
	ds_read_b128 v[206:209], v140 offset:7168
	s_add_i32 s51, s22, 2
	s_add_u32 s53, s20, 0x80
	s_addc_u32 s23, s21, 0
	s_add_i32 s56, 0, 0x10000
	s_cmp_eq_u32 s40, s22
	s_cselect_b32 s23, s5, s23
	s_cselect_b32 s22, s4, s53
	s_cselect_b32 s55, s19, s50
	s_cselect_b32 s54, s18, s49
	s_add_i32 s53, 0, 0x14000
	v_lshl_add_u64 v[198:199], s[20:21], 0, v[134:135]
	s_add_i32 m0, s29, 0xc000
	s_nop 0
	global_load_lds_dwordx4 v[198:199], off
	v_lshl_add_u64 v[198:199], s[20:21], 0, v[136:137]
	s_add_i32 m0, s29, 0xe000
	s_nop 0
	global_load_lds_dwordx4 v[198:199], off
	s_waitcnt vmcnt(8)
	s_waitcnt lgkmcnt(0)
	s_setprio 1
	s_barrier
	v_mfma_f32_16x16x32_bf16 v[124:127], v[142:145], v[174:177], v[124:127]
	v_mfma_f32_16x16x32_bf16 v[120:123], v[150:153], v[174:177], v[120:123]
	v_mfma_f32_16x16x32_bf16 v[108:111], v[142:145], v[182:185], v[108:111]
	v_mfma_f32_16x16x32_bf16 v[104:107], v[150:153], v[182:185], v[104:107]
	v_mfma_f32_16x16x32_bf16 v[92:95], v[142:145], v[190:193], v[92:95]
	v_mfma_f32_16x16x32_bf16 v[88:91], v[150:153], v[190:193], v[88:91]
	v_mfma_f32_16x16x32_bf16 v[76:79], v[142:145], v[202:205], v[76:79]
	v_mfma_f32_16x16x32_bf16 v[72:75], v[150:153], v[202:205], v[72:75]
	v_mfma_f32_16x16x32_bf16 v[124:127], v[146:149], v[178:181], v[124:127]
	v_mfma_f32_16x16x32_bf16 v[120:123], v[154:157], v[178:181], v[120:123]
	v_mfma_f32_16x16x32_bf16 v[108:111], v[146:149], v[186:189], v[108:111]
	v_mfma_f32_16x16x32_bf16 v[104:107], v[154:157], v[186:189], v[104:107]
	v_mfma_f32_16x16x32_bf16 v[92:95], v[146:149], v[194:197], v[92:95]
	v_mfma_f32_16x16x32_bf16 v[88:91], v[154:157], v[194:197], v[88:91]
	v_mfma_f32_16x16x32_bf16 v[76:79], v[146:149], v[206:209], v[76:79]
	v_mfma_f32_16x16x32_bf16 v[72:75], v[154:157], v[206:209], v[72:75]
	s_setprio 0
	s_setprio 1
	v_mfma_f32_16x16x32_bf16 v[116:119], v[158:161], v[174:177], v[116:119]
	v_mfma_f32_16x16x32_bf16 v[112:115], v[166:169], v[174:177], v[112:115]
	v_mfma_f32_16x16x32_bf16 v[100:103], v[158:161], v[182:185], v[100:103]
	v_mfma_f32_16x16x32_bf16 v[96:99], v[166:169], v[182:185], v[96:99]
	v_mfma_f32_16x16x32_bf16 v[84:87], v[158:161], v[190:193], v[84:87]
	v_mfma_f32_16x16x32_bf16 v[80:83], v[166:169], v[190:193], v[80:83]
	v_mfma_f32_16x16x32_bf16 v[68:71], v[158:161], v[202:205], v[68:71]
	v_mfma_f32_16x16x32_bf16 v[64:67], v[166:169], v[202:205], v[64:67]
	v_mfma_f32_16x16x32_bf16 v[116:119], v[162:165], v[178:181], v[116:119]
	v_mfma_f32_16x16x32_bf16 v[112:115], v[170:173], v[178:181], v[112:115]
	v_mfma_f32_16x16x32_bf16 v[100:103], v[162:165], v[186:189], v[100:103]
	v_mfma_f32_16x16x32_bf16 v[96:99], v[170:173], v[186:189], v[96:99]
	v_mfma_f32_16x16x32_bf16 v[84:87], v[162:165], v[194:197], v[84:87]
	v_mfma_f32_16x16x32_bf16 v[80:83], v[170:173], v[194:197], v[80:83]
	v_mfma_f32_16x16x32_bf16 v[68:71], v[162:165], v[206:209], v[68:71]
	v_mfma_f32_16x16x32_bf16 v[64:67], v[170:173], v[206:209], v[64:67]
	s_barrier
	s_setprio 0
	ds_read_b128 v[174:177], v140 offset:16384
	ds_read_b128 v[178:181], v140 offset:17408
	ds_read_b128 v[182:185], v140 offset:18432
	ds_read_b128 v[186:189], v140 offset:19456
	ds_read_b128 v[190:193], v140 offset:20480
	ds_read_b128 v[194:197], v140 offset:21504
	ds_read_b128 v[202:205], v140 offset:22528
	ds_read_b128 v[206:209], v140 offset:23552
	s_add_i32 s56, s56, s28
	v_lshl_add_u64 v[198:199], s[54:55], 0, v[200:201]
	s_mov_b32 m0, s56
	s_nop 0
	global_load_lds_dwordx4 v[198:199], off
	s_add_i32 m0, s56, 0x2000
	v_lshl_add_u64 v[212:213], s[54:55], 0, v[128:129]
	s_add_u32 s54, s54, s8
	s_addc_u32 s55, s55, s9
	s_add_i32 s53, s53, s28
	global_load_lds_dwordx4 v[212:213], off
	v_lshl_add_u64 v[214:215], s[54:55], 0, v[200:201]
	s_mov_b32 m0, s53
	v_lshl_add_u64 v[216:217], s[54:55], 0, v[128:129]
	global_load_lds_dwordx4 v[214:215], off
	s_add_i32 m0, s53, 0x2000
	v_lshl_add_u64 v[218:219], s[22:23], 0, v[132:133]
	global_load_lds_dwordx4 v[216:217], off
	s_mov_b32 m0, s29
	v_lshl_add_u64 v[220:221], s[22:23], 0, v[130:131]
	global_load_lds_dwordx4 v[218:219], off
	s_mov_b32 m0, s30
	s_nop 0
	global_load_lds_dwordx4 v[220:221], off
	s_waitcnt vmcnt(8)
	s_waitcnt lgkmcnt(0)
	s_setprio 1
	s_barrier
	v_mfma_f32_16x16x32_bf16 v[60:63], v[142:145], v[174:177], v[60:63]
	v_mfma_f32_16x16x32_bf16 v[56:59], v[150:153], v[174:177], v[56:59]
	v_mfma_f32_16x16x32_bf16 v[44:47], v[142:145], v[182:185], v[44:47]
	v_mfma_f32_16x16x32_bf16 v[40:43], v[150:153], v[182:185], v[40:43]
	v_mfma_f32_16x16x32_bf16 v[28:31], v[142:145], v[190:193], v[28:31]
	v_mfma_f32_16x16x32_bf16 v[24:27], v[150:153], v[190:193], v[24:27]
	v_mfma_f32_16x16x32_bf16 v[12:15], v[142:145], v[202:205], v[12:15]
	v_mfma_f32_16x16x32_bf16 v[8:11], v[150:153], v[202:205], v[8:11]
	v_mfma_f32_16x16x32_bf16 v[60:63], v[146:149], v[178:181], v[60:63]
	v_mfma_f32_16x16x32_bf16 v[56:59], v[154:157], v[178:181], v[56:59]
	v_mfma_f32_16x16x32_bf16 v[44:47], v[146:149], v[186:189], v[44:47]
	v_mfma_f32_16x16x32_bf16 v[40:43], v[154:157], v[186:189], v[40:43]
	v_mfma_f32_16x16x32_bf16 v[28:31], v[146:149], v[194:197], v[28:31]
	v_mfma_f32_16x16x32_bf16 v[24:27], v[154:157], v[194:197], v[24:27]
	v_mfma_f32_16x16x32_bf16 v[12:15], v[146:149], v[206:209], v[12:15]
	v_mfma_f32_16x16x32_bf16 v[8:11], v[154:157], v[206:209], v[8:11]
	s_setprio 0
	s_setprio 1
	v_mfma_f32_16x16x32_bf16 v[52:55], v[158:161], v[174:177], v[52:55]
	v_mfma_f32_16x16x32_bf16 v[48:51], v[166:169], v[174:177], v[48:51]
	v_mfma_f32_16x16x32_bf16 v[36:39], v[158:161], v[182:185], v[36:39]
	v_mfma_f32_16x16x32_bf16 v[32:35], v[166:169], v[182:185], v[32:35]
	v_mfma_f32_16x16x32_bf16 v[20:23], v[158:161], v[190:193], v[20:23]
	v_mfma_f32_16x16x32_bf16 v[16:19], v[166:169], v[190:193], v[16:19]
	v_mfma_f32_16x16x32_bf16 v[4:7], v[158:161], v[202:205], v[4:7]
	v_mfma_f32_16x16x32_bf16 v[0:3], v[166:169], v[202:205], v[0:3]
	v_mfma_f32_16x16x32_bf16 v[52:55], v[162:165], v[178:181], v[52:55]
	v_mfma_f32_16x16x32_bf16 v[48:51], v[170:173], v[178:181], v[48:51]
	v_mfma_f32_16x16x32_bf16 v[36:39], v[162:165], v[186:189], v[36:39]
	v_mfma_f32_16x16x32_bf16 v[32:35], v[170:173], v[186:189], v[32:35]
	v_mfma_f32_16x16x32_bf16 v[20:23], v[162:165], v[194:197], v[20:23]
	v_mfma_f32_16x16x32_bf16 v[16:19], v[170:173], v[194:197], v[16:19]
	v_mfma_f32_16x16x32_bf16 v[4:7], v[162:165], v[206:209], v[4:7]
	v_mfma_f32_16x16x32_bf16 v[0:3], v[170:173], v[206:209], v[0:3]
	s_barrier
	s_setprio 0
	ds_read_b128 v[142:145], v248
	ds_read_b128 v[146:149], v248 offset:1024
	ds_read_b128 v[150:153], v248 offset:2048
	ds_read_b128 v[154:157], v248 offset:3072
	ds_read_b128 v[158:161], v249
	ds_read_b128 v[162:165], v249 offset:1024
	ds_read_b128 v[166:169], v249 offset:2048
	ds_read_b128 v[170:173], v249 offset:3072
	ds_read_b128 v[174:177], v140 offset:32768
	ds_read_b128 v[178:181], v140 offset:33792
	ds_read_b128 v[182:185], v140 offset:34816
	ds_read_b128 v[186:189], v140 offset:35840
	ds_read_b128 v[190:193], v140 offset:36864
	ds_read_b128 v[194:197], v140 offset:37888
	ds_read_b128 v[202:205], v140 offset:38912
	ds_read_b128 v[206:209], v140 offset:39936
	s_add_i32 s53, 0, 0x18000
	s_add_i32 s54, 0, 0x1c000
	s_add_u32 s22, s22, s8
	s_addc_u32 s23, s23, s9
	s_mov_b32 m0, s31
	v_lshl_add_u64 v[222:223], s[22:23], 0, v[132:133]
	global_load_lds_dwordx4 v[222:223], off
	v_lshl_add_u64 v[222:223], s[22:23], 0, v[130:131]
	s_mov_b32 m0, s33
	s_nop 0
	global_load_lds_dwordx4 v[222:223], off
	s_waitcnt vmcnt(8)
	s_waitcnt lgkmcnt(0)
	s_setprio 1
	s_barrier
	v_mfma_f32_16x16x32_bf16 v[124:127], v[142:145], v[174:177], v[124:127]
	v_mfma_f32_16x16x32_bf16 v[120:123], v[150:153], v[174:177], v[120:123]
	v_mfma_f32_16x16x32_bf16 v[108:111], v[142:145], v[182:185], v[108:111]
	v_mfma_f32_16x16x32_bf16 v[104:107], v[150:153], v[182:185], v[104:107]
	v_mfma_f32_16x16x32_bf16 v[92:95], v[142:145], v[190:193], v[92:95]
	v_mfma_f32_16x16x32_bf16 v[88:91], v[150:153], v[190:193], v[88:91]
	v_mfma_f32_16x16x32_bf16 v[76:79], v[142:145], v[202:205], v[76:79]
	v_mfma_f32_16x16x32_bf16 v[72:75], v[150:153], v[202:205], v[72:75]
	v_mfma_f32_16x16x32_bf16 v[124:127], v[146:149], v[178:181], v[124:127]
	v_mfma_f32_16x16x32_bf16 v[120:123], v[154:157], v[178:181], v[120:123]
	v_mfma_f32_16x16x32_bf16 v[108:111], v[146:149], v[186:189], v[108:111]
	v_mfma_f32_16x16x32_bf16 v[104:107], v[154:157], v[186:189], v[104:107]
	v_mfma_f32_16x16x32_bf16 v[92:95], v[146:149], v[194:197], v[92:95]
	v_mfma_f32_16x16x32_bf16 v[88:91], v[154:157], v[194:197], v[88:91]
	v_mfma_f32_16x16x32_bf16 v[76:79], v[146:149], v[206:209], v[76:79]
	v_mfma_f32_16x16x32_bf16 v[72:75], v[154:157], v[206:209], v[72:75]
	s_setprio 0
	s_setprio 1
	v_mfma_f32_16x16x32_bf16 v[116:119], v[158:161], v[174:177], v[116:119]
	v_mfma_f32_16x16x32_bf16 v[112:115], v[166:169], v[174:177], v[112:115]
	v_mfma_f32_16x16x32_bf16 v[100:103], v[158:161], v[182:185], v[100:103]
	v_mfma_f32_16x16x32_bf16 v[96:99], v[166:169], v[182:185], v[96:99]
	v_mfma_f32_16x16x32_bf16 v[84:87], v[158:161], v[190:193], v[84:87]
	v_mfma_f32_16x16x32_bf16 v[80:83], v[166:169], v[190:193], v[80:83]
	v_mfma_f32_16x16x32_bf16 v[68:71], v[158:161], v[202:205], v[68:71]
	v_mfma_f32_16x16x32_bf16 v[64:67], v[166:169], v[202:205], v[64:67]
	v_mfma_f32_16x16x32_bf16 v[116:119], v[162:165], v[178:181], v[116:119]
	v_mfma_f32_16x16x32_bf16 v[112:115], v[170:173], v[178:181], v[112:115]
	v_mfma_f32_16x16x32_bf16 v[100:103], v[162:165], v[186:189], v[100:103]
	v_mfma_f32_16x16x32_bf16 v[96:99], v[170:173], v[186:189], v[96:99]
	v_mfma_f32_16x16x32_bf16 v[84:87], v[162:165], v[194:197], v[84:87]
	v_mfma_f32_16x16x32_bf16 v[80:83], v[170:173], v[194:197], v[80:83]
	v_mfma_f32_16x16x32_bf16 v[68:71], v[162:165], v[206:209], v[68:71]
	v_mfma_f32_16x16x32_bf16 v[64:67], v[170:173], v[206:209], v[64:67]
	s_barrier
	s_setprio 0
	ds_read_b128 v[174:177], v140 offset:49152
	ds_read_b128 v[178:181], v140 offset:50176
	ds_read_b128 v[182:185], v140 offset:51200
	ds_read_b128 v[186:189], v140 offset:52224
	ds_read_b128 v[190:193], v140 offset:53248
	ds_read_b128 v[194:197], v140 offset:54272
	ds_read_b128 v[202:205], v140 offset:55296
	ds_read_b128 v[206:209], v140 offset:56320
	s_add_i32 s22, s53, s28
	v_lshl_add_u64 v[198:199], v[198:199], 0, s[64:65]
	s_mov_b32 m0, s22
	s_nop 0
	global_load_lds_dwordx4 v[198:199], off
	v_lshl_add_u64 v[198:199], v[212:213], 0, s[64:65]
	s_add_i32 m0, s22, 0x2000
	s_add_i32 s22, s54, s28
	global_load_lds_dwordx4 v[198:199], off
	v_lshl_add_u64 v[198:199], v[214:215], 0, s[64:65]
	s_mov_b32 m0, s22
	s_nop 0
	global_load_lds_dwordx4 v[198:199], off
	v_lshl_add_u64 v[198:199], v[216:217], 0, s[64:65]
	s_add_i32 m0, s22, 0x2000
	s_nop 0
	global_load_lds_dwordx4 v[198:199], off
	v_lshl_add_u64 v[198:199], v[218:219], 0, s[64:65]
	s_mov_b32 m0, s36
	s_nop 0
	global_load_lds_dwordx4 v[198:199], off
	v_lshl_add_u64 v[198:199], v[220:221], 0, s[64:65]
	s_mov_b32 m0, s37
	s_nop 0
	global_load_lds_dwordx4 v[198:199], off
	s_waitcnt vmcnt(8)
	s_waitcnt lgkmcnt(0)
	s_setprio 1
	s_barrier
	v_mfma_f32_16x16x32_bf16 v[60:63], v[142:145], v[174:177], v[60:63]
	v_mfma_f32_16x16x32_bf16 v[56:59], v[150:153], v[174:177], v[56:59]
	v_mfma_f32_16x16x32_bf16 v[44:47], v[142:145], v[182:185], v[44:47]
	v_mfma_f32_16x16x32_bf16 v[40:43], v[150:153], v[182:185], v[40:43]
	v_mfma_f32_16x16x32_bf16 v[28:31], v[142:145], v[190:193], v[28:31]
	v_mfma_f32_16x16x32_bf16 v[24:27], v[150:153], v[190:193], v[24:27]
	v_mfma_f32_16x16x32_bf16 v[12:15], v[142:145], v[202:205], v[12:15]
	v_mfma_f32_16x16x32_bf16 v[8:11], v[150:153], v[202:205], v[8:11]
	v_mfma_f32_16x16x32_bf16 v[60:63], v[146:149], v[178:181], v[60:63]
	v_mfma_f32_16x16x32_bf16 v[56:59], v[154:157], v[178:181], v[56:59]
	v_mfma_f32_16x16x32_bf16 v[44:47], v[146:149], v[186:189], v[44:47]
	v_mfma_f32_16x16x32_bf16 v[40:43], v[154:157], v[186:189], v[40:43]
	v_mfma_f32_16x16x32_bf16 v[28:31], v[146:149], v[194:197], v[28:31]
	v_mfma_f32_16x16x32_bf16 v[24:27], v[154:157], v[194:197], v[24:27]
	v_mfma_f32_16x16x32_bf16 v[12:15], v[146:149], v[206:209], v[12:15]
	v_mfma_f32_16x16x32_bf16 v[8:11], v[154:157], v[206:209], v[8:11]
	s_setprio 0
	s_setprio 1
	v_mfma_f32_16x16x32_bf16 v[52:55], v[158:161], v[174:177], v[52:55]
	v_mfma_f32_16x16x32_bf16 v[48:51], v[166:169], v[174:177], v[48:51]
	v_mfma_f32_16x16x32_bf16 v[36:39], v[158:161], v[182:185], v[36:39]
	v_mfma_f32_16x16x32_bf16 v[32:35], v[166:169], v[182:185], v[32:35]
	v_mfma_f32_16x16x32_bf16 v[20:23], v[158:161], v[190:193], v[20:23]
	v_mfma_f32_16x16x32_bf16 v[16:19], v[166:169], v[190:193], v[16:19]
	v_mfma_f32_16x16x32_bf16 v[4:7], v[158:161], v[202:205], v[4:7]
	v_mfma_f32_16x16x32_bf16 v[0:3], v[166:169], v[202:205], v[0:3]
	v_mfma_f32_16x16x32_bf16 v[52:55], v[162:165], v[178:181], v[52:55]
	v_mfma_f32_16x16x32_bf16 v[48:51], v[170:173], v[178:181], v[48:51]
	v_mfma_f32_16x16x32_bf16 v[36:39], v[162:165], v[186:189], v[36:39]
	v_mfma_f32_16x16x32_bf16 v[32:35], v[170:173], v[186:189], v[32:35]
	v_mfma_f32_16x16x32_bf16 v[20:23], v[162:165], v[194:197], v[20:23]
	v_mfma_f32_16x16x32_bf16 v[16:19], v[170:173], v[194:197], v[16:19]
	v_mfma_f32_16x16x32_bf16 v[4:7], v[162:165], v[206:209], v[4:7]
	v_mfma_f32_16x16x32_bf16 v[0:3], v[170:173], v[206:209], v[0:3]
	s_barrier
	s_setprio 0
	s_add_u32 s20, s20, 0x100
	s_addc_u32 s21, s21, 0
	s_add_u32 s49, s49, 0x100
	s_addc_u32 s50, s50, 0
	s_cmp_ge_i32 s51, s34
	s_mov_b32 s22, s51
	s_cbranch_scc0 .LBB0_1149
	s_movk_i32 s53, 0xc000
	s_mov_b64 s[54:55], 0x800

.LBB0_1248:
	s_add_u32 s7, s82, 0x100
	s_addc_u32 s23, s83, 0
	s_mov_b32 s24, -2
	v_mov_b32_e32 v0, v212
	v_mov_b32_e32 v1, v212
	s_waitcnt lgkmcnt(0)
	v_mov_b32_e32 v2, v212
	v_mov_b32_e32 v3, v212
	v_mov_b32_e32 v4, v212
	v_mov_b32_e32 v5, v212
	v_mov_b32_e32 v6, v212
	v_mov_b32_e32 v7, v212
	v_mov_b32_e32 v8, v212
	v_mov_b32_e32 v9, v212
	v_mov_b32_e32 v10, v212
	v_mov_b32_e32 v11, v212
	v_mov_b32_e32 v12, v212
	v_mov_b32_e32 v13, v212
	v_mov_b32_e32 v14, v212
	v_mov_b32_e32 v15, v212
	v_mov_b32_e32 v16, v212
	v_mov_b32_e32 v17, v212
	v_mov_b32_e32 v18, v212
	v_mov_b32_e32 v19, v212
	v_mov_b32_e32 v20, v212
	v_mov_b32_e32 v21, v212
	v_mov_b32_e32 v22, v212
	v_mov_b32_e32 v23, v212
	v_mov_b32_e32 v24, v212
	v_mov_b32_e32 v25, v212
	v_mov_b32_e32 v26, v212
	v_mov_b32_e32 v27, v212
	v_mov_b32_e32 v28, v212
	v_mov_b32_e32 v29, v212
	v_mov_b32_e32 v30, v212
	v_mov_b32_e32 v31, v212
	v_mov_b32_e32 v32, v212
	v_mov_b32_e32 v33, v212
	v_mov_b32_e32 v34, v212
	v_mov_b32_e32 v35, v212
	v_mov_b32_e32 v36, v212
	v_mov_b32_e32 v37, v212
	v_mov_b32_e32 v38, v212
	v_mov_b32_e32 v39, v212
	v_mov_b32_e32 v40, v212
	v_mov_b32_e32 v41, v212
	v_mov_b32_e32 v42, v212
	v_mov_b32_e32 v43, v212
	v_mov_b32_e32 v44, v212
	v_mov_b32_e32 v45, v212
	v_mov_b32_e32 v46, v212
	v_mov_b32_e32 v47, v212
	v_mov_b32_e32 v48, v212
	v_mov_b32_e32 v49, v212
	v_mov_b32_e32 v50, v212
	v_mov_b32_e32 v51, v212
	v_mov_b32_e32 v52, v212
	v_mov_b32_e32 v53, v212
	v_mov_b32_e32 v54, v212
	v_mov_b32_e32 v55, v212
	v_mov_b32_e32 v56, v212
	v_mov_b32_e32 v57, v212
	v_mov_b32_e32 v58, v212
	v_mov_b32_e32 v59, v212
	v_mov_b32_e32 v60, v212
	v_mov_b32_e32 v61, v212
	v_mov_b32_e32 v62, v212
	v_mov_b32_e32 v63, v212
	v_mov_b32_e32 v64, v212
	v_mov_b32_e32 v65, v212
	v_mov_b32_e32 v66, v212
	v_mov_b32_e32 v67, v212
	v_mov_b32_e32 v68, v212
	v_mov_b32_e32 v69, v212
	v_mov_b32_e32 v70, v212
	v_mov_b32_e32 v71, v212
	v_mov_b32_e32 v72, v212
	v_mov_b32_e32 v73, v212
	v_mov_b32_e32 v74, v212
	v_mov_b32_e32 v75, v212
	v_mov_b32_e32 v88, v212
	v_mov_b32_e32 v89, v212
	v_mov_b32_e32 v90, v212
	v_mov_b32_e32 v91, v212
	v_mov_b32_e32 v96, v212
	v_mov_b32_e32 v97, v212
	v_mov_b32_e32 v98, v212
	v_mov_b32_e32 v99, v212
	v_mov_b32_e32 v100, v212
	v_mov_b32_e32 v101, v212
	v_mov_b32_e32 v102, v212
	v_mov_b32_e32 v103, v212
	v_mov_b32_e32 v104, v212
	v_mov_b32_e32 v105, v212
	v_mov_b32_e32 v106, v212
	v_mov_b32_e32 v107, v212
	v_mov_b32_e32 v108, v212
	v_mov_b32_e32 v109, v212
	v_mov_b32_e32 v110, v212
	v_mov_b32_e32 v111, v212
	v_mov_b32_e32 v128, v212
	v_mov_b32_e32 v129, v212
	v_mov_b32_e32 v130, v212
	v_mov_b32_e32 v131, v212
	v_mov_b32_e32 v132, v212
	v_mov_b32_e32 v133, v212
	v_mov_b32_e32 v134, v212
	v_mov_b32_e32 v135, v212
	v_mov_b32_e32 v136, v212
	v_mov_b32_e32 v137, v212
	v_mov_b32_e32 v138, v212
	v_mov_b32_e32 v139, v212
	v_mov_b32_e32 v140, v212
	v_mov_b32_e32 v141, v212
	v_mov_b32_e32 v142, v212
	v_mov_b32_e32 v143, v212
	v_mov_b32_e32 v144, v212
	v_mov_b32_e32 v145, v212
	v_mov_b32_e32 v146, v212
	v_mov_b32_e32 v147, v212
	v_mov_b32_e32 v148, v212
	v_mov_b32_e32 v149, v212
	v_mov_b32_e32 v150, v212
	v_mov_b32_e32 v151, v212
	v_mov_b32_e32 v156, v212
	v_mov_b32_e32 v157, v212
	v_mov_b32_e32 v158, v212
	v_mov_b32_e32 v159, v212
	v_mov_b32_e32 v164, v212
	v_mov_b32_e32 v165, v212
	v_mov_b32_e32 v166, v212
	v_mov_b32_e32 v167, v212
	v_add_u32_e32 v246, 0x10000, v213
	v_add_u32_e32 v247, 0x14000, v213
	v_add_u32_e32 v248, 0x18000, v213
	v_add_u32_e32 v249, 0x1c000, v213
.LBB0_1249:
	ds_read_b128 v[76:79], v246
	ds_read_b128 v[80:83], v246 offset:1024
	ds_read_b128 v[84:87], v246 offset:2048
	ds_read_b128 v[92:95], v246 offset:3072
	ds_read_b128 v[112:115], v247
	ds_read_b128 v[116:119], v247 offset:1024
	ds_read_b128 v[120:123], v247 offset:2048
	ds_read_b128 v[124:127], v247 offset:3072
	ds_read_b128 v[152:155], v206
	ds_read_b128 v[160:163], v206 offset:1024
	ds_read_b128 v[168:171], v206 offset:2048
	ds_read_b128 v[172:175], v206 offset:3072
	ds_read_b128 v[176:179], v206 offset:4096
	ds_read_b128 v[180:183], v206 offset:5120
	ds_read_b128 v[184:187], v206 offset:6144
	ds_read_b128 v[188:191], v206 offset:7168
	s_add_u32 s4, s74, 0x100
	s_addc_u32 s5, s75, 0
	s_add_i32 s25, 0, 0x10000
	s_cmpk_eq_i32 s24, 0x54
	s_cselect_b32 vcc_hi, s81, s5
	s_cselect_b32 vcc_lo, s80, s4
	s_cselect_b32 s83, s79, s23
	s_cselect_b32 s82, s78, s7
	s_add_i32 s28, 0, 0x14000
	v_lshl_add_u64 v[192:193], s[74:75], 0, v[222:223]
	s_add_i32 m0, s85, 0xc000
	s_nop 0
	global_load_lds_dwordx4 v[192:193], off
	v_lshl_add_u64 v[192:193], s[74:75], 0, v[224:225]
	s_add_i32 m0, s85, 0xe000
	s_nop 0
	global_load_lds_dwordx4 v[192:193], off
	s_waitcnt vmcnt(8)
	s_waitcnt lgkmcnt(0)
	s_setprio 1
	s_barrier
	v_mfma_f32_16x16x32_bf16 v[164:167], v[76:79], v[152:155], v[164:167]
	v_mfma_f32_16x16x32_bf16 v[156:159], v[84:87], v[152:155], v[156:159]
	v_mfma_f32_16x16x32_bf16 v[148:151], v[76:79], v[168:171], v[148:151]
	v_mfma_f32_16x16x32_bf16 v[144:147], v[84:87], v[168:171], v[144:147]
	v_mfma_f32_16x16x32_bf16 v[140:143], v[76:79], v[176:179], v[140:143]
	v_mfma_f32_16x16x32_bf16 v[136:139], v[84:87], v[176:179], v[136:139]
	v_mfma_f32_16x16x32_bf16 v[132:135], v[76:79], v[184:187], v[132:135]
	v_mfma_f32_16x16x32_bf16 v[128:131], v[84:87], v[184:187], v[128:131]
	v_mfma_f32_16x16x32_bf16 v[164:167], v[80:83], v[160:163], v[164:167]
	v_mfma_f32_16x16x32_bf16 v[156:159], v[92:95], v[160:163], v[156:159]
	v_mfma_f32_16x16x32_bf16 v[148:151], v[80:83], v[172:175], v[148:151]
	v_mfma_f32_16x16x32_bf16 v[144:147], v[92:95], v[172:175], v[144:147]
	v_mfma_f32_16x16x32_bf16 v[140:143], v[80:83], v[180:183], v[140:143]
	v_mfma_f32_16x16x32_bf16 v[136:139], v[92:95], v[180:183], v[136:139]
	v_mfma_f32_16x16x32_bf16 v[132:135], v[80:83], v[188:191], v[132:135]
	v_mfma_f32_16x16x32_bf16 v[128:131], v[92:95], v[188:191], v[128:131]
	s_setprio 0
	s_setprio 1
	v_mfma_f32_16x16x32_bf16 v[108:111], v[112:115], v[152:155], v[108:111]
	v_mfma_f32_16x16x32_bf16 v[104:107], v[120:123], v[152:155], v[104:107]
	v_mfma_f32_16x16x32_bf16 v[100:103], v[112:115], v[168:171], v[100:103]
	v_mfma_f32_16x16x32_bf16 v[96:99], v[120:123], v[168:171], v[96:99]
	v_mfma_f32_16x16x32_bf16 v[88:91], v[112:115], v[176:179], v[88:91]
	v_mfma_f32_16x16x32_bf16 v[72:75], v[120:123], v[176:179], v[72:75]
	v_mfma_f32_16x16x32_bf16 v[68:71], v[112:115], v[184:187], v[68:71]
	v_mfma_f32_16x16x32_bf16 v[64:67], v[120:123], v[184:187], v[64:67]
	v_mfma_f32_16x16x32_bf16 v[108:111], v[116:119], v[160:163], v[108:111]
	v_mfma_f32_16x16x32_bf16 v[104:107], v[124:127], v[160:163], v[104:107]
	v_mfma_f32_16x16x32_bf16 v[100:103], v[116:119], v[172:175], v[100:103]
	v_mfma_f32_16x16x32_bf16 v[96:99], v[124:127], v[172:175], v[96:99]
	v_mfma_f32_16x16x32_bf16 v[88:91], v[116:119], v[180:183], v[88:91]
	v_mfma_f32_16x16x32_bf16 v[72:75], v[124:127], v[180:183], v[72:75]
	v_mfma_f32_16x16x32_bf16 v[68:71], v[116:119], v[188:191], v[68:71]
	v_mfma_f32_16x16x32_bf16 v[64:67], v[124:127], v[188:191], v[64:67]
	s_barrier
	s_setprio 0
	ds_read_b128 v[152:155], v206 offset:16384
	ds_read_b128 v[160:163], v206 offset:17408
	ds_read_b128 v[168:171], v206 offset:18432
	ds_read_b128 v[172:175], v206 offset:19456
	ds_read_b128 v[176:179], v206 offset:20480
	ds_read_b128 v[180:183], v206 offset:21504
	ds_read_b128 v[184:187], v206 offset:22528
	ds_read_b128 v[188:191], v206 offset:23552
	s_add_i32 s25, s25, s56
	v_lshl_add_u64 v[192:193], s[82:83], 0, v[216:217]
	s_mov_b32 m0, s25
	s_nop 0
	global_load_lds_dwordx4 v[192:193], off
	s_add_i32 m0, s25, 0x2000
	s_add_u32 s74, s82, 0x160000
	v_lshl_add_u64 v[194:195], s[82:83], 0, v[220:221]
	s_addc_u32 s75, s83, 0
	s_add_i32 s25, s28, s56
	global_load_lds_dwordx4 v[194:195], off
	v_lshl_add_u64 v[196:197], s[74:75], 0, v[216:217]
	s_mov_b32 m0, s25
	v_lshl_add_u64 v[198:199], vcc, 0, v[218:219]
	global_load_lds_dwordx4 v[196:197], off
	v_lshl_add_u64 v[196:197], s[74:75], 0, v[220:221]
	s_add_i32 m0, s25, 0x2000
	s_nop 0
	global_load_lds_dwordx4 v[196:197], off
	v_lshl_add_u64 v[196:197], vcc, 0, v[214:215]
	s_mov_b32 m0, s85
	s_nop 0
	global_load_lds_dwordx4 v[196:197], off
	s_mov_b32 m0, s53
	s_nop 0
	global_load_lds_dwordx4 v[198:199], off
	s_waitcnt vmcnt(8)
	s_waitcnt lgkmcnt(0)
	s_setprio 1
	s_barrier
	v_mfma_f32_16x16x32_bf16 v[60:63], v[76:79], v[152:155], v[60:63]
	v_mfma_f32_16x16x32_bf16 v[56:59], v[84:87], v[152:155], v[56:59]
	v_mfma_f32_16x16x32_bf16 v[52:55], v[76:79], v[168:171], v[52:55]
	v_mfma_f32_16x16x32_bf16 v[48:51], v[84:87], v[168:171], v[48:51]
	v_mfma_f32_16x16x32_bf16 v[44:47], v[76:79], v[176:179], v[44:47]
	v_mfma_f32_16x16x32_bf16 v[40:43], v[84:87], v[176:179], v[40:43]
	v_mfma_f32_16x16x32_bf16 v[36:39], v[76:79], v[184:187], v[36:39]
	v_mfma_f32_16x16x32_bf16 v[32:35], v[84:87], v[184:187], v[32:35]
	v_mfma_f32_16x16x32_bf16 v[60:63], v[80:83], v[160:163], v[60:63]
	v_mfma_f32_16x16x32_bf16 v[56:59], v[92:95], v[160:163], v[56:59]
	v_mfma_f32_16x16x32_bf16 v[52:55], v[80:83], v[172:175], v[52:55]
	v_mfma_f32_16x16x32_bf16 v[48:51], v[92:95], v[172:175], v[48:51]
	v_mfma_f32_16x16x32_bf16 v[44:47], v[80:83], v[180:183], v[44:47]
	v_mfma_f32_16x16x32_bf16 v[40:43], v[92:95], v[180:183], v[40:43]
	v_mfma_f32_16x16x32_bf16 v[36:39], v[80:83], v[188:191], v[36:39]
	v_mfma_f32_16x16x32_bf16 v[32:35], v[92:95], v[188:191], v[32:35]
	s_setprio 0
	s_setprio 1
	v_mfma_f32_16x16x32_bf16 v[28:31], v[112:115], v[152:155], v[28:31]
	v_mfma_f32_16x16x32_bf16 v[24:27], v[120:123], v[152:155], v[24:27]
	v_mfma_f32_16x16x32_bf16 v[20:23], v[112:115], v[168:171], v[20:23]
	v_mfma_f32_16x16x32_bf16 v[16:19], v[120:123], v[168:171], v[16:19]
	v_mfma_f32_16x16x32_bf16 v[12:15], v[112:115], v[176:179], v[12:15]
	v_mfma_f32_16x16x32_bf16 v[8:11], v[120:123], v[176:179], v[8:11]
	v_mfma_f32_16x16x32_bf16 v[4:7], v[112:115], v[184:187], v[4:7]
	v_mfma_f32_16x16x32_bf16 v[0:3], v[120:123], v[184:187], v[0:3]
	v_mfma_f32_16x16x32_bf16 v[28:31], v[116:119], v[160:163], v[28:31]
	v_mfma_f32_16x16x32_bf16 v[24:27], v[124:127], v[160:163], v[24:27]
	v_mfma_f32_16x16x32_bf16 v[20:23], v[116:119], v[172:175], v[20:23]
	v_mfma_f32_16x16x32_bf16 v[16:19], v[124:127], v[172:175], v[16:19]
	v_mfma_f32_16x16x32_bf16 v[12:15], v[116:119], v[180:183], v[12:15]
	v_mfma_f32_16x16x32_bf16 v[8:11], v[124:127], v[180:183], v[8:11]
	v_mfma_f32_16x16x32_bf16 v[4:7], v[116:119], v[188:191], v[4:7]
	v_mfma_f32_16x16x32_bf16 v[0:3], v[124:127], v[188:191], v[0:3]
	s_barrier
	s_setprio 0
	ds_read_b128 v[76:79], v248
	ds_read_b128 v[80:83], v248 offset:1024
	ds_read_b128 v[84:87], v248 offset:2048
	ds_read_b128 v[92:95], v248 offset:3072
	ds_read_b128 v[112:115], v249
	ds_read_b128 v[116:119], v249 offset:1024
	ds_read_b128 v[120:123], v249 offset:2048
	ds_read_b128 v[124:127], v249 offset:3072
	ds_read_b128 v[152:155], v206 offset:32768
	ds_read_b128 v[160:163], v206 offset:33792
	ds_read_b128 v[168:171], v206 offset:34816
	ds_read_b128 v[172:175], v206 offset:35840
	ds_read_b128 v[176:179], v206 offset:36864
	ds_read_b128 v[180:183], v206 offset:37888
	ds_read_b128 v[184:187], v206 offset:38912
	ds_read_b128 v[188:191], v206 offset:39936
	s_add_i32 s25, 0, 0x18000
	s_add_i32 s28, 0, 0x1c000
	s_add_u32 s74, vcc_lo, 0x160000
	s_addc_u32 s75, vcc_hi, 0
	s_mov_b32 m0, s84
	v_lshl_add_u64 v[202:203], s[74:75], 0, v[214:215]
	global_load_lds_dwordx4 v[202:203], off
	v_lshl_add_u64 v[202:203], s[74:75], 0, v[218:219]
	s_mov_b32 m0, s26
	s_nop 0
	global_load_lds_dwordx4 v[202:203], off
	s_waitcnt vmcnt(8)
	s_waitcnt lgkmcnt(0)
	s_setprio 1
	s_barrier
	v_mfma_f32_16x16x32_bf16 v[164:167], v[76:79], v[152:155], v[164:167]
	v_mfma_f32_16x16x32_bf16 v[156:159], v[84:87], v[152:155], v[156:159]
	v_mfma_f32_16x16x32_bf16 v[148:151], v[76:79], v[168:171], v[148:151]
	v_mfma_f32_16x16x32_bf16 v[144:147], v[84:87], v[168:171], v[144:147]
	v_mfma_f32_16x16x32_bf16 v[140:143], v[76:79], v[176:179], v[140:143]
	v_mfma_f32_16x16x32_bf16 v[136:139], v[84:87], v[176:179], v[136:139]
	v_mfma_f32_16x16x32_bf16 v[132:135], v[76:79], v[184:187], v[132:135]
	v_mfma_f32_16x16x32_bf16 v[128:131], v[84:87], v[184:187], v[128:131]
	v_mfma_f32_16x16x32_bf16 v[164:167], v[80:83], v[160:163], v[164:167]
	v_mfma_f32_16x16x32_bf16 v[156:159], v[92:95], v[160:163], v[156:159]
	v_mfma_f32_16x16x32_bf16 v[148:151], v[80:83], v[172:175], v[148:151]
	v_mfma_f32_16x16x32_bf16 v[144:147], v[92:95], v[172:175], v[144:147]
	v_mfma_f32_16x16x32_bf16 v[140:143], v[80:83], v[180:183], v[140:143]
	v_mfma_f32_16x16x32_bf16 v[136:139], v[92:95], v[180:183], v[136:139]
	v_mfma_f32_16x16x32_bf16 v[132:135], v[80:83], v[188:191], v[132:135]
	v_mfma_f32_16x16x32_bf16 v[128:131], v[92:95], v[188:191], v[128:131]
	s_setprio 0
	s_setprio 1
	v_mfma_f32_16x16x32_bf16 v[108:111], v[112:115], v[152:155], v[108:111]
	v_mfma_f32_16x16x32_bf16 v[104:107], v[120:123], v[152:155], v[104:107]
	v_mfma_f32_16x16x32_bf16 v[100:103], v[112:115], v[168:171], v[100:103]
	v_mfma_f32_16x16x32_bf16 v[96:99], v[120:123], v[168:171], v[96:99]
	v_mfma_f32_16x16x32_bf16 v[88:91], v[112:115], v[176:179], v[88:91]
	v_mfma_f32_16x16x32_bf16 v[72:75], v[120:123], v[176:179], v[72:75]
	v_mfma_f32_16x16x32_bf16 v[68:71], v[112:115], v[184:187], v[68:71]
	v_mfma_f32_16x16x32_bf16 v[64:67], v[120:123], v[184:187], v[64:67]
	v_mfma_f32_16x16x32_bf16 v[108:111], v[116:119], v[160:163], v[108:111]
	v_mfma_f32_16x16x32_bf16 v[104:107], v[124:127], v[160:163], v[104:107]
	v_mfma_f32_16x16x32_bf16 v[100:103], v[116:119], v[172:175], v[100:103]
	v_mfma_f32_16x16x32_bf16 v[96:99], v[124:127], v[172:175], v[96:99]
	v_mfma_f32_16x16x32_bf16 v[88:91], v[116:119], v[180:183], v[88:91]
	v_mfma_f32_16x16x32_bf16 v[72:75], v[124:127], v[180:183], v[72:75]
	v_mfma_f32_16x16x32_bf16 v[68:71], v[116:119], v[188:191], v[68:71]
	v_mfma_f32_16x16x32_bf16 v[64:67], v[124:127], v[188:191], v[64:67]
	s_barrier
	s_setprio 0
	ds_read_b128 v[152:155], v206 offset:49152
	ds_read_b128 v[160:163], v206 offset:50176
	ds_read_b128 v[168:171], v206 offset:51200
	ds_read_b128 v[172:175], v206 offset:52224
	ds_read_b128 v[176:179], v206 offset:53248
	ds_read_b128 v[180:183], v206 offset:54272
	ds_read_b128 v[184:187], v206 offset:55296
	ds_read_b128 v[188:191], v206 offset:56320
	s_add_i32 s25, s25, s56
	v_lshl_add_u64 v[192:193], v[192:193], 0, s[64:65]
	s_mov_b32 m0, s25
	s_nop 0
	global_load_lds_dwordx4 v[192:193], off
	s_add_i32 m0, s25, 0x2000
	s_add_u32 s74, s82, 0x160080
	v_lshl_add_u64 v[192:193], v[194:195], 0, s[64:65]
	s_addc_u32 s75, s83, 0
	s_add_i32 s25, s28, s56
	global_load_lds_dwordx4 v[192:193], off
	v_lshl_add_u64 v[192:193], s[74:75], 0, v[216:217]
	s_mov_b32 m0, s25
	s_nop 0
	global_load_lds_dwordx4 v[192:193], off
	v_lshl_add_u64 v[192:193], s[74:75], 0, v[220:221]
	s_add_i32 m0, s25, 0x2000
	s_nop 0
	global_load_lds_dwordx4 v[192:193], off
	v_lshl_add_u64 v[192:193], v[196:197], 0, s[64:65]
	s_mov_b32 m0, s27
	s_nop 0
	global_load_lds_dwordx4 v[192:193], off
	v_lshl_add_u64 v[192:193], v[198:199], 0, s[64:65]
	s_mov_b32 m0, s42
	s_nop 0
	global_load_lds_dwordx4 v[192:193], off
	s_waitcnt vmcnt(8)
	s_waitcnt lgkmcnt(0)
	s_setprio 1
	s_barrier
	v_mfma_f32_16x16x32_bf16 v[60:63], v[76:79], v[152:155], v[60:63]
	v_mfma_f32_16x16x32_bf16 v[56:59], v[84:87], v[152:155], v[56:59]
	v_mfma_f32_16x16x32_bf16 v[52:55], v[76:79], v[168:171], v[52:55]
	v_mfma_f32_16x16x32_bf16 v[48:51], v[84:87], v[168:171], v[48:51]
	v_mfma_f32_16x16x32_bf16 v[44:47], v[76:79], v[176:179], v[44:47]
	v_mfma_f32_16x16x32_bf16 v[40:43], v[84:87], v[176:179], v[40:43]
	v_mfma_f32_16x16x32_bf16 v[36:39], v[76:79], v[184:187], v[36:39]
	v_mfma_f32_16x16x32_bf16 v[32:35], v[84:87], v[184:187], v[32:35]
	v_mfma_f32_16x16x32_bf16 v[60:63], v[80:83], v[160:163], v[60:63]
	v_mfma_f32_16x16x32_bf16 v[56:59], v[92:95], v[160:163], v[56:59]
	v_mfma_f32_16x16x32_bf16 v[52:55], v[80:83], v[172:175], v[52:55]
	v_mfma_f32_16x16x32_bf16 v[48:51], v[92:95], v[172:175], v[48:51]
	v_mfma_f32_16x16x32_bf16 v[44:47], v[80:83], v[180:183], v[44:47]
	v_mfma_f32_16x16x32_bf16 v[40:43], v[92:95], v[180:183], v[40:43]
	v_mfma_f32_16x16x32_bf16 v[36:39], v[80:83], v[188:191], v[36:39]
	v_mfma_f32_16x16x32_bf16 v[32:35], v[92:95], v[188:191], v[32:35]
	s_setprio 0
	s_setprio 1
	v_mfma_f32_16x16x32_bf16 v[28:31], v[112:115], v[152:155], v[28:31]
	v_mfma_f32_16x16x32_bf16 v[24:27], v[120:123], v[152:155], v[24:27]
	v_mfma_f32_16x16x32_bf16 v[20:23], v[112:115], v[168:171], v[20:23]
	v_mfma_f32_16x16x32_bf16 v[16:19], v[120:123], v[168:171], v[16:19]
	v_mfma_f32_16x16x32_bf16 v[12:15], v[112:115], v[176:179], v[12:15]
	v_mfma_f32_16x16x32_bf16 v[8:11], v[120:123], v[176:179], v[8:11]
	v_mfma_f32_16x16x32_bf16 v[4:7], v[112:115], v[184:187], v[4:7]
	v_mfma_f32_16x16x32_bf16 v[0:3], v[120:123], v[184:187], v[0:3]
	v_mfma_f32_16x16x32_bf16 v[28:31], v[116:119], v[160:163], v[28:31]
	v_mfma_f32_16x16x32_bf16 v[24:27], v[124:127], v[160:163], v[24:27]
	v_mfma_f32_16x16x32_bf16 v[20:23], v[116:119], v[172:175], v[20:23]
	v_mfma_f32_16x16x32_bf16 v[16:19], v[124:127], v[172:175], v[16:19]
	v_mfma_f32_16x16x32_bf16 v[12:15], v[116:119], v[180:183], v[12:15]
	v_mfma_f32_16x16x32_bf16 v[8:11], v[124:127], v[180:183], v[8:11]
	v_mfma_f32_16x16x32_bf16 v[4:7], v[116:119], v[188:191], v[4:7]
	v_mfma_f32_16x16x32_bf16 v[0:3], v[124:127], v[188:191], v[0:3]
	s_barrier
	s_setprio 0
	s_add_i32 s24, s24, 2
	s_add_u32 s7, s7, 0x100
	s_addc_u32 s23, s23, 0
	s_cmpk_gt_u32 s24, 0x55
	s_mov_b64 s[74:75], s[4:5]
	s_cbranch_scc0 .LBB0_1249
	v_readlane_b32 s4, v254, 60
	v_readlane_b32 s5, v254, 61
	s_and_b64 vcc, exec, s[4:5]
	s_cbranch_vccz .LBB0_1252
	s_barrier
